# P5/P8 row loops trimmed: fused v_add_f32_dpp hops, dead lgkmcnt waits removed
# baseline (speedup 1.0000x reference)
; __device__ __forceinline__ float bflo(unsigned u) { return __uint_as_float(u << 16); }
; __device__ __forceinline__ float bfhi(unsigned u) { return __uint_as_float(u & 0xffff0000u); }
; template <int NR, bool XBF, bool WOUT, bool WXB = true>
; __device__ __forceinline__ void rows_final(const float* xp, const float* xs, const bf16_t* __restrict__ Y, const float* __restrict__ ss, const float* __restrict__ gpost, float* out, bf16_t* xb, float* rs, int row0, int lane) {
;     ...
;     for (int r = 0; r < NR; ++r) { const int row = row0 + r;
;         const float* xrow = (row < NP_TOK) ? xp + (size_t)row * DM : xs + (size_t)(row - NP_TOK) * DM;
;         ssl[r] = (lane < 32) ? ss[(size_t)row * 32 + lane] : 0.f;
; #pragma unroll
;         for (int j = 0; j < 4; ++j) {
;             if (XBF) { const u32x2 xw = *((const u32x2*)(xb + (size_t)row * DM) + lane + 64 * j); v[r][j] = (f32x4){bflo(xw.x), bfhi(xw.x), bflo(xw.y), bfhi(xw.y)}; }
;             else v[r][j] = *((const f32x4*)xrow + lane + 64 * j);
;             yy[r][j] = *((const u32x2*)(Y + (size_t)row * DM) + lane + 64 * j); } }
.LBB0_611:
	v_mov_b32_e32 v88, 0
	v_lshl_add_u64 v[30:31], s[0:1], 0, v[18:19]
	v_mov_b32_e32 v34, 0
	s_and_saveexec_b64 s[2:3], s[4:5]
	s_cbranch_execz .LBB0_613
	v_add_co_u32_e32 v22, vcc, 0x3b7a0000, v30
	s_nop 0
	v_addc_co_u32_e32 v23, vcc, 0, v31, vcc
	global_load_dword v34, v[22:23], off
.LBB0_613:
	s_or_b64 exec, exec, s[2:3]
	v_lshl_add_u64 v[22:23], s[0:1], 0, v[20:21]
	v_add_co_u32_e32 v24, vcc, 0x2d000000, v22
	s_nop 1
	v_addc_co_u32_e32 v25, vcc, 0, v23, vcc
	v_add_co_u32_e32 v36, vcc, 0xf000000, v22
	s_nop 1
	v_addc_co_u32_e32 v37, vcc, 0, v23, vcc
	global_load_dwordx2 v[32:33], v[24:25], off
	global_load_dwordx2 v[28:29], v[24:25], off offset:512
	global_load_dwordx2 v[26:27], v[24:25], off offset:1024
	s_nop 0
	global_load_dwordx2 v[24:25], v[24:25], off offset:1536
	s_nop 0
	global_load_dwordx2 v[78:79], v[36:37], off
	global_load_dwordx2 v[76:77], v[36:37], off offset:512
	global_load_dwordx2 v[74:75], v[36:37], off offset:1024
	global_load_dwordx2 v[72:73], v[36:37], off offset:1536
	s_and_saveexec_b64 s[2:3], s[4:5]
	s_cbranch_execz .LBB0_615
	v_add_co_u32_e32 v36, vcc, 0x3b7a0000, v30
	s_nop 1
	v_addc_co_u32_e32 v37, vcc, 0, v31, vcc
	global_load_dword v88, v[36:37], off offset:128

; __device__ __forceinline__ unsigned cvtpk(float lo, float hi) { f32x2 v = {lo, hi}; bf16x2_t b = __builtin_convertvector(v, bf16x2_t); return __builtin_bit_cast(unsigned, b); }
; __device__ __forceinline__ float bflo(unsigned u) { return __uint_as_float(u << 16); }
; __device__ __forceinline__ float bfhi(unsigned u) { return __uint_as_float(u & 0xffff0000u); }
; __device__ __forceinline__ float wave_sum(float v) {
; #pragma unroll
;     for (int o = 1; o < 64; o <<= 1) v += __shfl_xor(v, o);
;     return v;
; template <int NR, bool XBF, bool WOUT, bool WXB = true>
; __device__ __forceinline__ void rows_final(const float* xp, const float* xs, const bf16_t* __restrict__ Y, const float* __restrict__ ss, const float* __restrict__ gpost, float* out, bf16_t* xb, float* rs, int row0, int lane) {
;     ...
;     for (int r = 0; r < NR; ++r) { const int row = row0 + r;
;         const float rn = rsqrtf(wave_sum(ssl[r]) * (1.f / DM) + EPS); float s = 0.f;
; #pragma unroll
;         for (int j = 0; j < 4; ++j) { const f32x4 yf = {bflo(yy[r][j].x), bfhi(yy[r][j].x), bflo(yy[r][j].y), bfhi(yy[r][j].y)};
;             v[r][j] = v[r][j] + yf * rn * g[j]; s += (v[r][j][0] * v[r][j][0] + v[r][j][1] * v[r][j][1]) + (v[r][j][2] * v[r][j][2] + v[r][j][3] * v[r][j][3]); }
;         s = wave_sum(s);
;         f32x4* oo = (f32x4*)(out + (size_t)row * DM) + lane; u32x2* o = (u32x2*)(xb + (size_t)row * DM) + lane;
; #pragma unroll
;         for (int j = 0; j < 4; ++j) { if (WOUT) oo[64 * j] = v[r][j]; if (WXB) { u32x2 w; w.x = cvtpk(v[r][j][0], v[r][j][1]); w.y = cvtpk(v[r][j][2], v[r][j][3]); o[64 * j] = w; } }
;         if (WXB && lane == 0) rs[row] = rsqrtf(s * (1.f / DM) + EPS); }
.LBB0_619:
	s_or_b64 exec, exec, s[2:3]
	s_waitcnt vmcnt(0)
	v_lshlrev_b32_e32 v94, 16, v28
	v_and_b32_e32 v95, 0xffff0000, v28
	v_lshlrev_b32_e32 v96, 16, v29
	v_and_b32_e32 v97, 0xffff0000, v29
	v_add_f32_dpp v28, v34, v34 quad_perm:[1,0,3,2] row_mask:0xf bank_mask:0xf
	v_lshlrev_b32_e32 v98, 16, v26
	v_and_b32_e32 v99, 0xffff0000, v26
	v_lshlrev_b32_e32 v100, 16, v27
	v_and_b32_e32 v101, 0xffff0000, v27
	v_add_f32_dpp v26, v28, v28 quad_perm:[2,3,0,1] row_mask:0xf bank_mask:0xf
	s_mov_b32 s2, 0x2d001000
	v_lshlrev_b32_e32 v102, 16, v24
	v_and_b32_e32 v103, 0xffff0000, v24
	v_add_co_u32_e32 v24, vcc, s2, v22
	v_add_f32_dpp v26, v26, v26 row_half_mirror row_mask:0xf bank_mask:0xf
	v_lshlrev_b32_e32 v104, 16, v25
	v_and_b32_e32 v105, 0xffff0000, v25
	v_addc_co_u32_e32 v25, vcc, 0, v23, vcc
	v_add_f32_dpp v26, v26, v26 row_mirror row_mask:0xf bank_mask:0xf
	v_mov_b32_e32 v27, v26
	v_mov_b32_e32 v254, v26
	s_nop 1
	v_permlane16_swap_b32_e32 v27, v254
	s_mov_b32 s2, 0xf001000
	v_lshlrev_b32_e32 v90, 16, v32
	v_and_b32_e32 v91, 0xffff0000, v32
	v_lshlrev_b32_e32 v92, 16, v33
	v_add_f32_e32 v26, v254, v27
	v_mov_b32_e32 v27, v26
	v_mov_b32_e32 v254, v26
	s_nop 1
	v_permlane32_swap_b32_e32 v27, v254
	v_and_b32_e32 v93, 0xffff0000, v33
	v_add_co_u32_e32 v106, vcc, s2, v22
	global_load_dwordx2 v[38:39], v[24:25], off offset:2048
	global_load_dwordx2 v[36:37], v[24:25], off offset:2560
	global_load_dwordx2 v[34:35], v[24:25], off offset:3072
	global_load_dwordx2 v[32:33], v[24:25], off offset:3584
	v_add_f32_e32 v24, v254, v27
	v_addc_co_u32_e32 v107, vcc, 0, v23, vcc
	v_fmamk_f32 v24, v24, 0x3a800000, v241
	v_mul_f32_e32 v25, 0x4b800000, v24
	v_cmp_gt_f32_e32 vcc, s21, v24
	v_lshlrev_b32_e32 v108, 16, v78
	v_and_b32_e32 v109, 0xffff0000, v78
	v_cndmask_b32_e32 v24, v24, v25, vcc
	v_rsq_f32_e32 v89, v24
	global_load_dwordx2 v[30:31], v[106:107], off offset:2048
	global_load_dwordx2 v[28:29], v[106:107], off offset:2560
	global_load_dwordx2 v[26:27], v[106:107], off offset:3072
	global_load_dwordx2 v[24:25], v[106:107], off offset:3584
	v_lshlrev_b32_e32 v78, 16, v79
	v_and_b32_e32 v79, 0xffff0000, v79
	v_mul_f32_e32 v106, 0x45800000, v89
	v_cndmask_b32_e32 v106, v89, v106, vcc
	v_pk_mul_f32 v[108:109], v[106:107], v[108:109] op_sel_hi:[0,1]
	v_pk_mul_f32 v[78:79], v[106:107], v[78:79] op_sel_hi:[0,1]
	v_pk_fma_f32 v[78:79], v[4:5], v[78:79], v[92:93]
	v_pk_fma_f32 v[90:91], v[2:3], v[108:109], v[90:91]
	v_mul_f32_e32 v92, v79, v79
	v_mul_f32_e32 v89, v91, v91
	v_fmac_f32_e32 v89, v90, v90
	v_fmac_f32_e32 v92, v78, v78
	v_add_f32_e32 v89, v89, v92
	v_lshlrev_b32_e32 v92, 16, v76
	v_and_b32_e32 v93, 0xffff0000, v76
	v_lshlrev_b32_e32 v76, 16, v77
	v_and_b32_e32 v77, 0xffff0000, v77
	v_pk_mul_f32 v[92:93], v[106:107], v[92:93] op_sel_hi:[0,1]
	v_pk_mul_f32 v[76:77], v[106:107], v[76:77] op_sel_hi:[0,1]
	v_pk_fma_f32 v[76:77], v[8:9], v[76:77], v[96:97]
	v_pk_fma_f32 v[92:93], v[6:7], v[92:93], v[94:95]
	v_mul_f32_e32 v95, v77, v77
	v_mul_f32_e32 v94, v93, v93
	v_fmac_f32_e32 v94, v92, v92
	v_fmac_f32_e32 v95, v76, v76
	v_add_f32_e32 v94, v94, v95
	v_add_f32_e32 v89, v89, v94
	v_lshlrev_b32_e32 v94, 16, v74
	v_and_b32_e32 v95, 0xffff0000, v74
	v_lshlrev_b32_e32 v74, 16, v75
	v_and_b32_e32 v75, 0xffff0000, v75
	v_pk_mul_f32 v[94:95], v[106:107], v[94:95] op_sel_hi:[0,1]
	v_pk_mul_f32 v[74:75], v[106:107], v[74:75] op_sel_hi:[0,1]
	v_pk_fma_f32 v[74:75], v[12:13], v[74:75], v[100:101]
	v_pk_fma_f32 v[94:95], v[10:11], v[94:95], v[98:99]
	v_mul_f32_e32 v97, v75, v75
	v_mul_f32_e32 v96, v95, v95
	v_fmac_f32_e32 v96, v94, v94
	v_fmac_f32_e32 v97, v74, v74
	v_add_f32_e32 v96, v96, v97
	v_add_f32_e32 v89, v96, v89
	v_lshlrev_b32_e32 v96, 16, v72
	v_and_b32_e32 v97, 0xffff0000, v72
	v_lshlrev_b32_e32 v72, 16, v73
	v_and_b32_e32 v73, 0xffff0000, v73
	v_pk_mul_f32 v[96:97], v[106:107], v[96:97] op_sel_hi:[0,1]
	v_pk_mul_f32 v[72:73], v[106:107], v[72:73] op_sel_hi:[0,1]
	v_pk_fma_f32 v[98:99], v[16:17], v[72:73], v[104:105]
	v_pk_fma_f32 v[96:97], v[14:15], v[96:97], v[102:103]
	v_mul_f32_e32 v73, v99, v99
	v_mul_f32_e32 v72, v97, v97
	v_fmac_f32_e32 v72, v96, v96
	v_fmac_f32_e32 v73, v98, v98
	v_add_f32_e32 v72, v72, v73
	v_add_f32_e32 v72, v72, v89
	s_mov_b64 s[2:3], 0x2d000000
	v_lshl_add_u64 v[100:101], v[22:23], 0, s[2:3]
	s_mov_b64 s[2:3], 0x2d000200
	v_lshl_add_u64 v[102:103], v[22:23], 0, s[2:3]
	v_add_f32_dpp v72, v72, v72 quad_perm:[1,0,3,2] row_mask:0xf bank_mask:0xf
	s_mov_b64 s[2:3], 0x2d000400
	v_lshl_add_u64 v[104:105], v[22:23], 0, s[2:3]
	s_mov_b64 s[2:3], 0x2d000600
	v_lshl_add_u64 v[106:107], v[22:23], 0, s[2:3]
	v_add_f32_dpp v72, v72, v72 quad_perm:[2,3,0,1] row_mask:0xf bank_mask:0xf
	v_cvt_pk_bf16_f32 v90, v90, v91
	v_cvt_pk_bf16_f32 v91, v78, v79
	v_cvt_pk_bf16_f32 v78, v92, v93
	v_cvt_pk_bf16_f32 v79, v76, v77
	v_add_f32_dpp v72, v72, v72 row_half_mirror row_mask:0xf bank_mask:0xf
	v_cvt_pk_bf16_f32 v76, v94, v95
	v_cvt_pk_bf16_f32 v77, v74, v75
	v_cvt_pk_bf16_f32 v74, v96, v97
	v_cvt_pk_bf16_f32 v75, v98, v99
	v_add_f32_dpp v72, v72, v72 row_mirror row_mask:0xf bank_mask:0xf
	v_mov_b32_e32 v73, v72
	v_mov_b32_e32 v254, v72
	s_nop 1
	v_permlane16_swap_b32_e32 v73, v254
	global_store_dwordx2 v[100:101], v[90:91], off
	global_store_dwordx2 v[102:103], v[78:79], off
	global_store_dwordx2 v[104:105], v[76:77], off
	global_store_dwordx2 v[106:107], v[74:75], off
	v_add_f32_e32 v72, v254, v73
	v_mov_b32_e32 v73, v72
	v_mov_b32_e32 v254, v72
	s_nop 1
	v_permlane32_swap_b32_e32 v73, v254
	s_and_saveexec_b64 s[2:3], s[6:7]
	s_cbranch_execz .LBB0_621
	v_add_f32_e32 v72, v254, v73
	v_fmamk_f32 v72, v72, 0x3a800000, v241
	v_mul_f32_e32 v73, 0x4b800000, v72
	v_cmp_gt_f32_e32 vcc, s21, v72
	s_add_u32 s11, s0, s12
	s_addc_u32 s15, s1, s13
	v_cndmask_b32_e32 v72, v72, v73, vcc
	v_rsq_f32_e32 v72, v72
	s_nop 0
	v_mul_f32_e32 v73, 0x45800000, v72
	v_cndmask_b32_e32 v74, v72, v73, vcc
	v_mov_b32_e32 v72, s11
	v_add_co_u32_e32 v72, vcc, 0x3b750000, v72
	v_mov_b32_e32 v73, s15
	s_nop 0
	v_addc_co_u32_e32 v73, vcc, 0, v73, vcc
	global_store_dword v[72:73], v74, off
; __device__ __forceinline__ unsigned cvtpk(float lo, float hi) { f32x2 v = {lo, hi}; bf16x2_t b = __builtin_convertvector(v, bf16x2_t); return __builtin_bit_cast(unsigned, b); }
; __device__ __forceinline__ float bflo(unsigned u) { return __uint_as_float(u << 16); }
; __device__ __forceinline__ float bfhi(unsigned u) { return __uint_as_float(u & 0xffff0000u); }
; __device__ __forceinline__ float wave_sum(float v) {
; #pragma unroll
;     for (int o = 1; o < 64; o <<= 1) v += __shfl_xor(v, o);
;     return v;
; template <int NR, bool XBF, bool WOUT, bool WXB = true>
; __device__ __forceinline__ void rows_final(const float* xp, const float* xs, const bf16_t* __restrict__ Y, const float* __restrict__ ss, const float* __restrict__ gpost, float* out, bf16_t* xb, float* rs, int row0, int lane) {
;     ...
;     for (int r = 0; r < NR; ++r) { const int row = row0 + r;
;         const float rn = rsqrtf(wave_sum(ssl[r]) * (1.f / DM) + EPS); float s = 0.f;
; #pragma unroll
;         for (int j = 0; j < 4; ++j) { const f32x4 yf = {bflo(yy[r][j].x), bfhi(yy[r][j].x), bflo(yy[r][j].y), bfhi(yy[r][j].y)};
;             v[r][j] = v[r][j] + yf * rn * g[j]; s += (v[r][j][0] * v[r][j][0] + v[r][j][1] * v[r][j][1]) + (v[r][j][2] * v[r][j][2] + v[r][j][3] * v[r][j][3]); }
;         s = wave_sum(s);
;         f32x4* oo = (f32x4*)(out + (size_t)row * DM) + lane; u32x2* o = (u32x2*)(xb + (size_t)row * DM) + lane;
; #pragma unroll
;         for (int j = 0; j < 4; ++j) { if (WOUT) oo[64 * j] = v[r][j]; if (WXB) { u32x2 w; w.x = cvtpk(v[r][j][0], v[r][j][1]); w.y = cvtpk(v[r][j][2], v[r][j][3]); o[64 * j] = w; } }
;         if (WXB && lane == 0) rs[row] = rsqrtf(s * (1.f / DM) + EPS); }
.LBB0_621:
	s_or_b64 exec, exec, s[2:3]
	v_and_b32_e32 v73, 0xffff0000, v70
	s_mov_b64 s[2:3], 0x2d000800
	v_add_f32_dpp v74, v88, v88 quad_perm:[1,0,3,2] row_mask:0xf bank_mask:0xf
	v_lshlrev_b32_e32 v72, 16, v70
	v_lshlrev_b32_e32 v70, 16, v71
	v_and_b32_e32 v71, 0xffff0000, v71
	v_add_f32_dpp v76, v74, v74 quad_perm:[2,3,0,1] row_mask:0xf bank_mask:0xf
	v_lshlrev_b32_e32 v74, 16, v68
	v_and_b32_e32 v75, 0xffff0000, v68
	v_lshlrev_b32_e32 v68, 16, v69
	v_and_b32_e32 v69, 0xffff0000, v69
	v_add_f32_dpp v78, v76, v76 row_half_mirror row_mask:0xf bank_mask:0xf
	v_lshlrev_b32_e32 v76, 16, v66
	v_and_b32_e32 v77, 0xffff0000, v66
	v_lshlrev_b32_e32 v66, 16, v67
	v_and_b32_e32 v67, 0xffff0000, v67
	v_add_f32_dpp v88, v78, v78 row_mirror row_mask:0xf bank_mask:0xf
	v_mov_b32_e32 v89, v88
	v_mov_b32_e32 v254, v88
	s_nop 1
	v_permlane16_swap_b32_e32 v89, v254
	v_lshlrev_b32_e32 v78, 16, v64
	v_and_b32_e32 v79, 0xffff0000, v64
	v_lshlrev_b32_e32 v64, 16, v65
	v_and_b32_e32 v65, 0xffff0000, v65
	v_add_f32_e32 v90, v254, v89
	v_mov_b32_e32 v91, v90
	v_mov_b32_e32 v254, v90
	s_nop 1
	v_permlane32_swap_b32_e32 v91, v254
	v_lshlrev_b32_e32 v88, 16, v62
	v_and_b32_e32 v89, 0xffff0000, v62
	v_lshlrev_b32_e32 v62, 16, v63
	v_and_b32_e32 v63, 0xffff0000, v63
	v_add_f32_e32 v90, v254, v91
	v_fmamk_f32 v90, v90, 0x3a800000, v241
	v_mul_f32_e32 v91, 0x4b800000, v90
	v_cmp_gt_f32_e32 vcc, s21, v90
	s_nop 1
	v_cndmask_b32_e32 v90, v90, v91, vcc
	v_rsq_f32_e32 v92, v90
	v_lshlrev_b32_e32 v90, 16, v60
	v_and_b32_e32 v91, 0xffff0000, v60
	v_mul_f32_e32 v60, 0x45800000, v92
	v_cndmask_b32_e32 v60, v92, v60, vcc
	v_pk_mul_f32 v[88:89], v[60:61], v[88:89] op_sel_hi:[0,1]
	v_pk_mul_f32 v[62:63], v[60:61], v[62:63] op_sel_hi:[0,1]
	v_pk_fma_f32 v[62:63], v[4:5], v[62:63], v[70:71]
	v_pk_fma_f32 v[70:71], v[2:3], v[88:89], v[72:73]
	v_mul_f32_e32 v73, v63, v63
	v_mul_f32_e32 v72, v71, v71
	v_fmac_f32_e32 v72, v70, v70
	v_fmac_f32_e32 v73, v62, v62
	v_add_f32_e32 v92, v72, v73
	v_lshlrev_b32_e32 v72, 16, v61
	v_and_b32_e32 v73, 0xffff0000, v61
	v_pk_mul_f32 v[88:89], v[60:61], v[90:91] op_sel_hi:[0,1]
	v_pk_mul_f32 v[72:73], v[60:61], v[72:73] op_sel_hi:[0,1]
	v_pk_fma_f32 v[68:69], v[8:9], v[72:73], v[68:69]
	v_pk_fma_f32 v[72:73], v[6:7], v[88:89], v[74:75]
	v_mul_f32_e32 v74, v69, v69
	v_mul_f32_e32 v61, v73, v73
	v_fmac_f32_e32 v61, v72, v72
	v_fmac_f32_e32 v74, v68, v68
	v_add_f32_e32 v61, v61, v74
	v_add_f32_e32 v61, v92, v61
	v_lshlrev_b32_e32 v74, 16, v58
	v_and_b32_e32 v75, 0xffff0000, v58
	v_lshlrev_b32_e32 v58, 16, v59
	v_and_b32_e32 v59, 0xffff0000, v59
	v_pk_mul_f32 v[74:75], v[60:61], v[74:75] op_sel_hi:[0,1]
	v_pk_mul_f32 v[58:59], v[60:61], v[58:59] op_sel_hi:[0,1]
	v_pk_fma_f32 v[58:59], v[12:13], v[58:59], v[66:67]
	v_pk_fma_f32 v[66:67], v[10:11], v[74:75], v[76:77]
	v_mul_f32_e32 v75, v59, v59
	v_mul_f32_e32 v74, v67, v67
	v_fmac_f32_e32 v74, v66, v66
	v_fmac_f32_e32 v75, v58, v58
	v_add_f32_e32 v74, v74, v75
	v_add_f32_e32 v76, v74, v61
	v_lshlrev_b32_e32 v74, 16, v56
	v_and_b32_e32 v75, 0xffff0000, v56
	v_lshlrev_b32_e32 v56, 16, v57
	v_and_b32_e32 v57, 0xffff0000, v57
	v_pk_mul_f32 v[74:75], v[60:61], v[74:75] op_sel_hi:[0,1]
	v_pk_mul_f32 v[56:57], v[60:61], v[56:57] op_sel_hi:[0,1]
	v_pk_fma_f32 v[60:61], v[16:17], v[56:57], v[64:65]
	v_pk_fma_f32 v[64:65], v[14:15], v[74:75], v[78:79]
	v_mul_f32_e32 v57, v61, v61
	v_mul_f32_e32 v56, v65, v65
	v_fmac_f32_e32 v56, v64, v64
	v_fmac_f32_e32 v57, v60, v60
	v_add_f32_e32 v56, v56, v57
	v_add_f32_e32 v56, v56, v76
	v_lshl_add_u64 v[74:75], v[22:23], 0, s[2:3]
	s_mov_b64 s[2:3], 0x2d000a00
	v_lshl_add_u64 v[76:77], v[22:23], 0, s[2:3]
	s_mov_b64 s[2:3], 0x2d000c00
	v_add_f32_dpp v56, v56, v56 quad_perm:[1,0,3,2] row_mask:0xf bank_mask:0xf
	v_lshl_add_u64 v[78:79], v[22:23], 0, s[2:3]
	s_mov_b64 s[2:3], 0x2d000e00
	v_cvt_pk_bf16_f32 v70, v70, v71
	v_cvt_pk_bf16_f32 v71, v62, v63
	v_add_f32_dpp v56, v56, v56 quad_perm:[2,3,0,1] row_mask:0xf bank_mask:0xf
	v_cvt_pk_bf16_f32 v62, v72, v73
	v_cvt_pk_bf16_f32 v63, v68, v69
	v_lshl_add_u64 v[88:89], v[22:23], 0, s[2:3]
	global_store_dwordx2 v[76:77], v[62:63], off
	v_add_f32_dpp v56, v56, v56 row_half_mirror row_mask:0xf bank_mask:0xf
	v_cvt_pk_bf16_f32 v62, v66, v67
	v_cvt_pk_bf16_f32 v63, v58, v59
	v_cvt_pk_bf16_f32 v58, v64, v65
	v_cvt_pk_bf16_f32 v59, v60, v61
	v_add_f32_dpp v56, v56, v56 row_mirror row_mask:0xf bank_mask:0xf
	v_mov_b32_e32 v57, v56
	v_mov_b32_e32 v254, v56
	s_nop 1
	v_permlane16_swap_b32_e32 v57, v254
	global_store_dwordx2 v[74:75], v[70:71], off
	global_store_dwordx2 v[78:79], v[62:63], off
	global_store_dwordx2 v[88:89], v[58:59], off
	v_add_f32_e32 v56, v254, v57
	v_mov_b32_e32 v57, v56
	v_mov_b32_e32 v254, v56
	s_nop 1
	v_permlane32_swap_b32_e32 v57, v254
	s_and_saveexec_b64 s[2:3], s[6:7]
	s_cbranch_execz .LBB0_623
	v_add_f32_e32 v56, v254, v57
	v_fmamk_f32 v56, v56, 0x3a800000, v241
	v_mul_f32_e32 v57, 0x4b800000, v56
	v_cmp_gt_f32_e32 vcc, s21, v56
	s_add_u32 s11, s0, s12
	s_addc_u32 s15, s1, s13
	v_cndmask_b32_e32 v56, v56, v57, vcc
	v_rsq_f32_e32 v56, v56
	s_nop 0
	v_mul_f32_e32 v57, 0x45800000, v56
	v_cndmask_b32_e32 v58, v56, v57, vcc
	v_mov_b32_e32 v56, s11
	v_add_co_u32_e32 v56, vcc, 0x3b750000, v56
	v_mov_b32_e32 v57, s15
	s_nop 0
	v_addc_co_u32_e32 v57, vcc, 0, v57, vcc
	global_store_dword v[56:57], v58, off offset:4
; __device__ __forceinline__ unsigned cvtpk(float lo, float hi) { f32x2 v = {lo, hi}; bf16x2_t b = __builtin_convertvector(v, bf16x2_t); return __builtin_bit_cast(unsigned, b); }
; __device__ __forceinline__ float bflo(unsigned u) { return __uint_as_float(u << 16); }
; __device__ __forceinline__ float bfhi(unsigned u) { return __uint_as_float(u & 0xffff0000u); }
; __device__ __forceinline__ float wave_sum(float v) {
; #pragma unroll
;     for (int o = 1; o < 64; o <<= 1) v += __shfl_xor(v, o);
;     return v;
; template <int NR, bool XBF, bool WOUT, bool WXB = true>
; __device__ __forceinline__ void rows_final(const float* xp, const float* xs, const bf16_t* __restrict__ Y, const float* __restrict__ ss, const float* __restrict__ gpost, float* out, bf16_t* xb, float* rs, int row0, int lane) {
;     ...
;     for (int r = 0; r < NR; ++r) { const int row = row0 + r;
;         const float rn = rsqrtf(wave_sum(ssl[r]) * (1.f / DM) + EPS); float s = 0.f;
; #pragma unroll
;         for (int j = 0; j < 4; ++j) { const f32x4 yf = {bflo(yy[r][j].x), bfhi(yy[r][j].x), bflo(yy[r][j].y), bfhi(yy[r][j].y)};
;             v[r][j] = v[r][j] + yf * rn * g[j]; s += (v[r][j][0] * v[r][j][0] + v[r][j][1] * v[r][j][1]) + (v[r][j][2] * v[r][j][2] + v[r][j][3] * v[r][j][3]); }
;         s = wave_sum(s);
;         f32x4* oo = (f32x4*)(out + (size_t)row * DM) + lane; u32x2* o = (u32x2*)(xb + (size_t)row * DM) + lane;
; #pragma unroll
;         for (int j = 0; j < 4; ++j) { if (WOUT) oo[64 * j] = v[r][j]; if (WXB) { u32x2 w; w.x = cvtpk(v[r][j][0], v[r][j][1]); w.y = cvtpk(v[r][j][2], v[r][j][3]); o[64 * j] = w; } }
;         if (WXB && lane == 0) rs[row] = rsqrtf(s * (1.f / DM) + EPS); }
.LBB0_623:
	s_or_b64 exec, exec, s[2:3]
	v_and_b32_e32 v57, 0xffff0000, v54
	s_mov_b64 s[2:3], 0x2d001000
	v_add_f32_dpp v58, v87, v87 quad_perm:[1,0,3,2] row_mask:0xf bank_mask:0xf
	v_lshlrev_b32_e32 v56, 16, v54
	v_lshlrev_b32_e32 v54, 16, v55
	v_and_b32_e32 v55, 0xffff0000, v55
	v_add_f32_dpp v60, v58, v58 quad_perm:[2,3,0,1] row_mask:0xf bank_mask:0xf
	v_lshlrev_b32_e32 v58, 16, v52
	v_and_b32_e32 v59, 0xffff0000, v52
	v_lshlrev_b32_e32 v52, 16, v53
	v_and_b32_e32 v53, 0xffff0000, v53
	v_add_f32_dpp v62, v60, v60 row_half_mirror row_mask:0xf bank_mask:0xf
	v_lshlrev_b32_e32 v60, 16, v50
	v_and_b32_e32 v61, 0xffff0000, v50
	v_lshlrev_b32_e32 v50, 16, v51
	v_and_b32_e32 v51, 0xffff0000, v51
	v_add_f32_dpp v64, v62, v62 row_mirror row_mask:0xf bank_mask:0xf
	v_mov_b32_e32 v65, v64
	v_mov_b32_e32 v254, v64
	s_nop 1
	v_permlane16_swap_b32_e32 v65, v254
	v_lshlrev_b32_e32 v62, 16, v48
	v_and_b32_e32 v63, 0xffff0000, v48
	v_lshlrev_b32_e32 v48, 16, v49
	v_and_b32_e32 v49, 0xffff0000, v49
	v_add_f32_e32 v66, v254, v65
	v_mov_b32_e32 v67, v66
	v_mov_b32_e32 v254, v66
	s_nop 1
	v_permlane32_swap_b32_e32 v67, v254
	v_lshlrev_b32_e32 v64, 16, v46
	v_and_b32_e32 v65, 0xffff0000, v46
	v_lshlrev_b32_e32 v46, 16, v47
	v_and_b32_e32 v47, 0xffff0000, v47
	v_add_f32_e32 v66, v254, v67
	v_fmamk_f32 v66, v66, 0x3a800000, v241
	v_mul_f32_e32 v67, 0x4b800000, v66
	v_cmp_gt_f32_e32 vcc, s21, v66
	s_nop 1
	v_cndmask_b32_e32 v66, v66, v67, vcc
	v_rsq_f32_e32 v68, v66
	v_lshlrev_b32_e32 v66, 16, v44
	v_and_b32_e32 v67, 0xffff0000, v44
	v_mul_f32_e32 v44, 0x45800000, v68
	v_cndmask_b32_e32 v44, v68, v44, vcc
	v_pk_mul_f32 v[64:65], v[44:45], v[64:65] op_sel_hi:[0,1]
	v_pk_mul_f32 v[46:47], v[44:45], v[46:47] op_sel_hi:[0,1]
	v_pk_fma_f32 v[46:47], v[4:5], v[46:47], v[54:55]
	v_pk_fma_f32 v[54:55], v[2:3], v[64:65], v[56:57]
	v_mul_f32_e32 v57, v47, v47
	v_mul_f32_e32 v56, v55, v55
	v_fmac_f32_e32 v56, v54, v54
	v_fmac_f32_e32 v57, v46, v46
	v_add_f32_e32 v68, v56, v57
	v_lshlrev_b32_e32 v56, 16, v45
	v_and_b32_e32 v57, 0xffff0000, v45
	v_pk_mul_f32 v[64:65], v[44:45], v[66:67] op_sel_hi:[0,1]
	v_pk_mul_f32 v[56:57], v[44:45], v[56:57] op_sel_hi:[0,1]
	v_pk_fma_f32 v[52:53], v[8:9], v[56:57], v[52:53]
	v_pk_fma_f32 v[56:57], v[6:7], v[64:65], v[58:59]
	v_mul_f32_e32 v58, v53, v53
	v_mul_f32_e32 v45, v57, v57
	v_fmac_f32_e32 v45, v56, v56
	v_fmac_f32_e32 v58, v52, v52
	v_add_f32_e32 v45, v45, v58
	v_add_f32_e32 v45, v68, v45
	v_lshlrev_b32_e32 v58, 16, v42
	v_and_b32_e32 v59, 0xffff0000, v42
	v_lshlrev_b32_e32 v42, 16, v43
	v_and_b32_e32 v43, 0xffff0000, v43
	v_pk_mul_f32 v[58:59], v[44:45], v[58:59] op_sel_hi:[0,1]
	v_pk_mul_f32 v[42:43], v[44:45], v[42:43] op_sel_hi:[0,1]
	v_pk_fma_f32 v[42:43], v[12:13], v[42:43], v[50:51]
	v_pk_fma_f32 v[50:51], v[10:11], v[58:59], v[60:61]
	v_mul_f32_e32 v59, v43, v43
	v_mul_f32_e32 v58, v51, v51
	v_fmac_f32_e32 v58, v50, v50
	v_fmac_f32_e32 v59, v42, v42
	v_add_f32_e32 v58, v58, v59
	v_add_f32_e32 v60, v58, v45
	v_lshlrev_b32_e32 v58, 16, v40
	v_and_b32_e32 v59, 0xffff0000, v40
	v_lshlrev_b32_e32 v40, 16, v41
	v_and_b32_e32 v41, 0xffff0000, v41
	v_pk_mul_f32 v[58:59], v[44:45], v[58:59] op_sel_hi:[0,1]
	v_pk_mul_f32 v[40:41], v[44:45], v[40:41] op_sel_hi:[0,1]
	v_pk_fma_f32 v[44:45], v[16:17], v[40:41], v[48:49]
	v_pk_fma_f32 v[48:49], v[14:15], v[58:59], v[62:63]
	v_mul_f32_e32 v41, v45, v45
	v_mul_f32_e32 v40, v49, v49
	v_fmac_f32_e32 v40, v48, v48
	v_fmac_f32_e32 v41, v44, v44
	v_add_f32_e32 v40, v40, v41
	v_add_f32_e32 v40, v40, v60
	v_lshl_add_u64 v[58:59], v[22:23], 0, s[2:3]
	s_mov_b64 s[2:3], 0x2d001200
	v_lshl_add_u64 v[60:61], v[22:23], 0, s[2:3]
	s_mov_b64 s[2:3], 0x2d001400
	v_add_f32_dpp v40, v40, v40 quad_perm:[1,0,3,2] row_mask:0xf bank_mask:0xf
	v_lshl_add_u64 v[62:63], v[22:23], 0, s[2:3]
	s_mov_b64 s[2:3], 0x2d001600
	v_cvt_pk_bf16_f32 v54, v54, v55
	v_cvt_pk_bf16_f32 v55, v46, v47
	v_add_f32_dpp v40, v40, v40 quad_perm:[2,3,0,1] row_mask:0xf bank_mask:0xf
	v_cvt_pk_bf16_f32 v46, v56, v57
	v_cvt_pk_bf16_f32 v47, v52, v53
	v_lshl_add_u64 v[64:65], v[22:23], 0, s[2:3]
	global_store_dwordx2 v[60:61], v[46:47], off
	v_add_f32_dpp v40, v40, v40 row_half_mirror row_mask:0xf bank_mask:0xf
	v_cvt_pk_bf16_f32 v46, v50, v51
	v_cvt_pk_bf16_f32 v47, v42, v43
	v_cvt_pk_bf16_f32 v42, v48, v49
	v_cvt_pk_bf16_f32 v43, v44, v45
	v_add_f32_dpp v40, v40, v40 row_mirror row_mask:0xf bank_mask:0xf
	v_mov_b32_e32 v41, v40
	v_mov_b32_e32 v254, v40
	s_nop 1
	v_permlane16_swap_b32_e32 v41, v254
	global_store_dwordx2 v[58:59], v[54:55], off
	global_store_dwordx2 v[62:63], v[46:47], off
	global_store_dwordx2 v[64:65], v[42:43], off
	v_add_f32_e32 v40, v254, v41
	v_mov_b32_e32 v41, v40
	v_mov_b32_e32 v254, v40
	s_nop 1
	v_permlane32_swap_b32_e32 v41, v254
	s_and_saveexec_b64 s[2:3], s[6:7]
	s_cbranch_execz .LBB0_625
	v_add_f32_e32 v40, v254, v41
	v_fmamk_f32 v40, v40, 0x3a800000, v241
	v_mul_f32_e32 v41, 0x4b800000, v40
	v_cmp_gt_f32_e32 vcc, s21, v40
	s_add_u32 s11, s0, s12
	s_addc_u32 s15, s1, s13
	v_cndmask_b32_e32 v40, v40, v41, vcc
	v_rsq_f32_e32 v40, v40
	s_nop 0
	v_mul_f32_e32 v41, 0x45800000, v40
	v_cndmask_b32_e32 v42, v40, v41, vcc
	v_mov_b32_e32 v40, s11
	v_add_co_u32_e32 v40, vcc, 0x3b750000, v40
	v_mov_b32_e32 v41, s15
	s_nop 0
	v_addc_co_u32_e32 v41, vcc, 0, v41, vcc
	global_store_dword v[40:41], v42, off offset:8
; __device__ __forceinline__ unsigned cvtpk(float lo, float hi) { f32x2 v = {lo, hi}; bf16x2_t b = __builtin_convertvector(v, bf16x2_t); return __builtin_bit_cast(unsigned, b); }
; __device__ __forceinline__ float bflo(unsigned u) { return __uint_as_float(u << 16); }
; __device__ __forceinline__ float bfhi(unsigned u) { return __uint_as_float(u & 0xffff0000u); }
; __device__ __forceinline__ float wave_sum(float v) {
; #pragma unroll
;     for (int o = 1; o < 64; o <<= 1) v += __shfl_xor(v, o);
;     return v;
; template <int NR, bool XBF, bool WOUT, bool WXB = true>
; __device__ __forceinline__ void rows_final(const float* xp, const float* xs, const bf16_t* __restrict__ Y, const float* __restrict__ ss, const float* __restrict__ gpost, float* out, bf16_t* xb, float* rs, int row0, int lane) {
;     ...
;     for (int r = 0; r < NR; ++r) { const int row = row0 + r;
;         const float rn = rsqrtf(wave_sum(ssl[r]) * (1.f / DM) + EPS); float s = 0.f;
; #pragma unroll
;         for (int j = 0; j < 4; ++j) { const f32x4 yf = {bflo(yy[r][j].x), bfhi(yy[r][j].x), bflo(yy[r][j].y), bfhi(yy[r][j].y)};
;             v[r][j] = v[r][j] + yf * rn * g[j]; s += (v[r][j][0] * v[r][j][0] + v[r][j][1] * v[r][j][1]) + (v[r][j][2] * v[r][j][2] + v[r][j][3] * v[r][j][3]); }
;         s = wave_sum(s);
;         f32x4* oo = (f32x4*)(out + (size_t)row * DM) + lane; u32x2* o = (u32x2*)(xb + (size_t)row * DM) + lane;
; #pragma unroll
;         for (int j = 0; j < 4; ++j) { if (WOUT) oo[64 * j] = v[r][j]; if (WXB) { u32x2 w; w.x = cvtpk(v[r][j][0], v[r][j][1]); w.y = cvtpk(v[r][j][2], v[r][j][3]); o[64 * j] = w; } }
;         if (WXB && lane == 0) rs[row] = rsqrtf(s * (1.f / DM) + EPS); }
.LBB0_625:
	s_or_b64 exec, exec, s[2:3]
	s_waitcnt vmcnt(0)
	v_and_b32_e32 v41, 0xffff0000, v38
	s_mov_b64 s[2:3], 0x2d001800
	v_add_f32_dpp v42, v86, v86 quad_perm:[1,0,3,2] row_mask:0xf bank_mask:0xf
	v_lshlrev_b32_e32 v40, 16, v38
	v_lshlrev_b32_e32 v38, 16, v39
	v_and_b32_e32 v39, 0xffff0000, v39
	v_add_f32_dpp v44, v42, v42 quad_perm:[2,3,0,1] row_mask:0xf bank_mask:0xf
	v_lshlrev_b32_e32 v42, 16, v36
	v_and_b32_e32 v43, 0xffff0000, v36
	v_lshlrev_b32_e32 v36, 16, v37
	v_and_b32_e32 v37, 0xffff0000, v37
	v_add_f32_dpp v46, v44, v44 row_half_mirror row_mask:0xf bank_mask:0xf
	v_lshlrev_b32_e32 v44, 16, v34
	v_and_b32_e32 v45, 0xffff0000, v34
	v_lshlrev_b32_e32 v34, 16, v35
	v_and_b32_e32 v35, 0xffff0000, v35
	v_add_f32_dpp v48, v46, v46 row_mirror row_mask:0xf bank_mask:0xf
	v_mov_b32_e32 v49, v48
	v_mov_b32_e32 v254, v48
	s_nop 1
	v_permlane16_swap_b32_e32 v49, v254
	v_lshlrev_b32_e32 v46, 16, v32
	v_and_b32_e32 v47, 0xffff0000, v32
	v_lshlrev_b32_e32 v32, 16, v33
	v_and_b32_e32 v33, 0xffff0000, v33
	v_add_f32_e32 v50, v254, v49
	v_mov_b32_e32 v51, v50
	v_mov_b32_e32 v254, v50
	s_nop 1
	v_permlane32_swap_b32_e32 v51, v254
	v_lshlrev_b32_e32 v48, 16, v30
	v_and_b32_e32 v49, 0xffff0000, v30
	v_lshlrev_b32_e32 v30, 16, v31
	v_and_b32_e32 v31, 0xffff0000, v31
	v_add_f32_e32 v50, v254, v51
	v_fmamk_f32 v50, v50, 0x3a800000, v241
	v_mul_f32_e32 v51, 0x4b800000, v50
	v_cmp_gt_f32_e32 vcc, s21, v50
	s_nop 1
	v_cndmask_b32_e32 v50, v50, v51, vcc
	v_rsq_f32_e32 v52, v50
	v_lshlrev_b32_e32 v50, 16, v28
	v_and_b32_e32 v51, 0xffff0000, v28
	v_mul_f32_e32 v28, 0x45800000, v52
	v_cndmask_b32_e32 v28, v52, v28, vcc
	v_pk_mul_f32 v[48:49], v[28:29], v[48:49] op_sel_hi:[0,1]
	v_pk_mul_f32 v[30:31], v[28:29], v[30:31] op_sel_hi:[0,1]
	v_pk_fma_f32 v[30:31], v[4:5], v[30:31], v[38:39]
	v_pk_fma_f32 v[38:39], v[2:3], v[48:49], v[40:41]
	v_mul_f32_e32 v41, v31, v31
	v_mul_f32_e32 v40, v39, v39
	v_fmac_f32_e32 v40, v38, v38
	v_fmac_f32_e32 v41, v30, v30
	v_add_f32_e32 v52, v40, v41
	v_lshlrev_b32_e32 v40, 16, v29
	v_and_b32_e32 v41, 0xffff0000, v29
	v_pk_mul_f32 v[48:49], v[28:29], v[50:51] op_sel_hi:[0,1]
	v_pk_mul_f32 v[40:41], v[28:29], v[40:41] op_sel_hi:[0,1]
	v_pk_fma_f32 v[36:37], v[8:9], v[40:41], v[36:37]
	v_pk_fma_f32 v[40:41], v[6:7], v[48:49], v[42:43]
	v_mul_f32_e32 v42, v37, v37
	v_mul_f32_e32 v29, v41, v41
	v_fmac_f32_e32 v29, v40, v40
	v_fmac_f32_e32 v42, v36, v36
	v_add_f32_e32 v29, v29, v42
	v_add_f32_e32 v29, v52, v29
	v_lshlrev_b32_e32 v42, 16, v26
	v_and_b32_e32 v43, 0xffff0000, v26
	v_lshlrev_b32_e32 v26, 16, v27
	v_and_b32_e32 v27, 0xffff0000, v27
	v_pk_mul_f32 v[42:43], v[28:29], v[42:43] op_sel_hi:[0,1]
	v_pk_mul_f32 v[26:27], v[28:29], v[26:27] op_sel_hi:[0,1]
	v_pk_fma_f32 v[26:27], v[12:13], v[26:27], v[34:35]
	v_pk_fma_f32 v[34:35], v[10:11], v[42:43], v[44:45]
	v_mul_f32_e32 v43, v27, v27
	v_mul_f32_e32 v42, v35, v35
	v_fmac_f32_e32 v42, v34, v34
	v_fmac_f32_e32 v43, v26, v26
	v_add_f32_e32 v42, v42, v43
	v_add_f32_e32 v44, v42, v29
	v_lshlrev_b32_e32 v42, 16, v24
	v_and_b32_e32 v43, 0xffff0000, v24
	v_lshlrev_b32_e32 v24, 16, v25
	v_and_b32_e32 v25, 0xffff0000, v25
	v_pk_mul_f32 v[42:43], v[28:29], v[42:43] op_sel_hi:[0,1]
	v_pk_mul_f32 v[24:25], v[28:29], v[24:25] op_sel_hi:[0,1]
	v_pk_fma_f32 v[24:25], v[16:17], v[24:25], v[32:33]
	v_pk_fma_f32 v[28:29], v[14:15], v[42:43], v[46:47]
	v_mul_f32_e32 v33, v25, v25
	v_mul_f32_e32 v32, v29, v29
	v_fmac_f32_e32 v32, v28, v28
	v_fmac_f32_e32 v33, v24, v24
	v_add_f32_e32 v32, v32, v33
	v_add_f32_e32 v32, v32, v44
	v_cvt_pk_bf16_f32 v38, v38, v39
	v_cvt_pk_bf16_f32 v39, v30, v31
	v_cvt_pk_bf16_f32 v30, v40, v41
	v_cvt_pk_bf16_f32 v31, v36, v37
	v_add_f32_dpp v32, v32, v32 quad_perm:[1,0,3,2] row_mask:0xf bank_mask:0xf
	s_nop 1
	v_add_f32_dpp v32, v32, v32 quad_perm:[2,3,0,1] row_mask:0xf bank_mask:0xf
	s_nop 1
	v_add_f32_dpp v32, v32, v32 row_half_mirror row_mask:0xf bank_mask:0xf
	s_nop 1
	v_add_f32_dpp v48, v32, v32 row_mirror row_mask:0xf bank_mask:0xf
	v_mov_b32_e32 v49, v48
	v_mov_b32_e32 v254, v48
	s_nop 1
	v_permlane16_swap_b32_e32 v49, v254
	v_lshl_add_u64 v[32:33], v[22:23], 0, s[2:3]
	s_mov_b64 s[2:3], 0x2d001a00
	v_lshl_add_u64 v[42:43], v[22:23], 0, s[2:3]
	s_mov_b64 s[2:3], 0x2d001c00
	v_lshl_add_u64 v[44:45], v[22:23], 0, s[2:3]
	s_mov_b64 s[2:3], 0x2d001e00
	v_lshl_add_u64 v[46:47], v[22:23], 0, s[2:3]
	v_add_f32_e32 v22, v254, v49
	v_mov_b32_e32 v23, v22
	v_mov_b32_e32 v254, v22
	s_nop 1
	v_permlane32_swap_b32_e32 v23, v254
	global_store_dwordx2 v[42:43], v[30:31], off
	v_cvt_pk_bf16_f32 v30, v34, v35
	v_cvt_pk_bf16_f32 v31, v26, v27
	v_cvt_pk_bf16_f32 v26, v28, v29
	v_cvt_pk_bf16_f32 v27, v24, v25
	global_store_dwordx2 v[32:33], v[38:39], off
	global_store_dwordx2 v[44:45], v[30:31], off
	global_store_dwordx2 v[46:47], v[26:27], off
	s_and_saveexec_b64 s[2:3], s[6:7]
	s_cbranch_execz .LBB0_610
	v_add_f32_e32 v22, v254, v23
	v_fmamk_f32 v22, v22, 0x3a800000, v241
	v_mul_f32_e32 v23, 0x4b800000, v22
	v_cmp_gt_f32_e32 vcc, s21, v22
	s_add_u32 s11, s0, s12
	s_addc_u32 s15, s1, s13
	v_cndmask_b32_e32 v22, v22, v23, vcc
	v_rsq_f32_e32 v22, v22
	s_nop 0
	v_mul_f32_e32 v23, 0x45800000, v22
	v_cndmask_b32_e32 v24, v22, v23, vcc
	v_mov_b32_e32 v22, s11
	v_add_co_u32_e32 v22, vcc, 0x3b750000, v22
	v_mov_b32_e32 v23, s15
	s_nop 0
	v_addc_co_u32_e32 v23, vcc, 0, v23, vcc
	global_store_dword v[22:23], v24, off offset:12
	s_branch .LBB0_610

; __device__ __forceinline__ float bflo(unsigned u) { return __uint_as_float(u << 16); }
; __device__ __forceinline__ float bfhi(unsigned u) { return __uint_as_float(u & 0xffff0000u); }
; template <int NR, bool XBF, bool WOUT, bool WXB = true>
; __device__ __forceinline__ void rows_final(const float* xp, const float* xs, const bf16_t* __restrict__ Y, const float* __restrict__ ss, const float* __restrict__ gpost, float* out, bf16_t* xb, float* rs, int row0, int lane) {
;     ...
;     for (int r = 0; r < NR; ++r) { const int row = row0 + r;
;         const float* xrow = (row < NP_TOK) ? xp + (size_t)row * DM : xs + (size_t)(row - NP_TOK) * DM;
;         ssl[r] = (lane < 32) ? ss[(size_t)row * 32 + lane] : 0.f;
; #pragma unroll
;         for (int j = 0; j < 4; ++j) {
;             if (XBF) { const u32x2 xw = *((const u32x2*)(xb + (size_t)row * DM) + lane + 64 * j); v[r][j] = (f32x4){bflo(xw.x), bfhi(xw.x), bflo(xw.y), bfhi(xw.y)}; }
;             else v[r][j] = *((const f32x4*)xrow + lane + 64 * j);
;             yy[r][j] = *((const u32x2*)(Y + (size_t)row * DM) + lane + 64 * j); } }
.LBB0_632:
	v_mov_b32_e32 v129, 0
	v_lshl_add_u64 v[18:19], s[0:1], 0, v[84:85]
	v_mov_b32_e32 v120, 0
	s_and_saveexec_b64 s[2:3], s[4:5]
	s_cbranch_execz .LBB0_634
	v_add_co_u32_e32 v20, vcc, 0x3b7a0000, v18
	s_nop 1
	v_addc_co_u32_e32 v21, vcc, 0, v19, vcc
	global_load_dword v120, v[20:21], off
.LBB0_634:
	s_or_b64 exec, exec, s[2:3]
	v_readlane_b32 s48, v253, 29
	s_add_i32 s2, s8, 0xffff0000
	v_readlane_b32 s49, v253, 30
	s_cmp_lt_i32 s8, 0x10000
	v_readlane_b32 s50, v253, 31
	v_readlane_b32 s51, v253, 32
	s_mov_b64 s[16:17], s[48:49]
	s_cselect_b32 s3, s9, 0
	s_cselect_b32 s2, s8, s2
	s_mov_b64 s[18:19], s[50:51]
	s_cselect_b32 s12, s17, s19
	s_cselect_b32 s13, s16, s18
	s_lshl_b64 s[2:3], s[2:3], 12
	s_add_u32 s2, s13, s2
	v_lshl_add_u64 v[90:91], s[0:1], 0, v[82:83]
	s_addc_u32 s3, s12, s3
	v_lshlrev_b32_e32 v20, 4, v0
	v_add_co_u32_e32 v22, vcc, 0xf000000, v90
	v_readlane_b32 s52, v253, 33
	v_addc_co_u32_e32 v23, vcc, 0, v91, vcc
	global_load_dwordx4 v[78:81], v20, s[2:3]
	global_load_dwordx4 v[74:77], v20, s[2:3] offset:1024
	global_load_dwordx4 v[70:73], v20, s[2:3] offset:2048
	global_load_dwordx4 v[66:69], v20, s[2:3] offset:3072
	global_load_dwordx2 v[118:119], v[22:23], off
	global_load_dwordx2 v[116:117], v[22:23], off offset:512
	global_load_dwordx2 v[114:115], v[22:23], off offset:1024
	global_load_dwordx2 v[112:113], v[22:23], off offset:1536
	v_readlane_b32 s53, v253, 34
	v_readlane_b32 s54, v253, 35
	v_readlane_b32 s55, v253, 36
	v_readlane_b32 s56, v253, 37
	v_readlane_b32 s57, v253, 38
	v_readlane_b32 s58, v253, 39
	v_readlane_b32 s59, v253, 40
	v_readlane_b32 s60, v253, 41
	v_readlane_b32 s61, v253, 42
	v_readlane_b32 s62, v253, 43
	v_readlane_b32 s63, v253, 44
	s_and_saveexec_b64 s[2:3], s[4:5]
	s_cbranch_execz .LBB0_636
	v_add_co_u32_e32 v22, vcc, 0x3b7a0000, v18
	s_nop 1
	v_addc_co_u32_e32 v23, vcc, 0, v19, vcc
	global_load_dword v129, v[22:23], off offset:128

; __device__ __forceinline__ unsigned cvtpk(float lo, float hi) { f32x2 v = {lo, hi}; bf16x2_t b = __builtin_convertvector(v, bf16x2_t); return __builtin_bit_cast(unsigned, b); }
; __device__ __forceinline__ float bflo(unsigned u) { return __uint_as_float(u << 16); }
; __device__ __forceinline__ float bfhi(unsigned u) { return __uint_as_float(u & 0xffff0000u); }
; template <int NR, bool XBF, bool WOUT, bool WXB = true>
; __device__ __forceinline__ void rows_final(const float* xp, const float* xs, const bf16_t* __restrict__ Y, const float* __restrict__ ss, const float* __restrict__ gpost, float* out, bf16_t* xb, float* rs, int row0, int lane) {
;     ...
;     for (int r = 0; r < NR; ++r) { const int row = row0 + r;
;         const float* xrow = (row < NP_TOK) ? xp + (size_t)row * DM : xs + (size_t)(row - NP_TOK) * DM;
;         ssl[r] = (lane < 32) ? ss[(size_t)row * 32 + lane] : 0.f;
; #pragma unroll
;         for (int j = 0; j < 4; ++j) {
;             if (XBF) { const u32x2 xw = *((const u32x2*)(xb + (size_t)row * DM) + lane + 64 * j); v[r][j] = (f32x4){bflo(xw.x), bfhi(xw.x), bflo(xw.y), bfhi(xw.y)}; }
;             else v[r][j] = *((const f32x4*)xrow + lane + 64 * j);
;             yy[r][j] = *((const u32x2*)(Y + (size_t)row * DM) + lane + 64 * j); } }
;     f32x4 g[4];
; #pragma unroll
;     for (int j = 0; j < 4; ++j) g[j] = *((const f32x4*)gpost + lane + 64 * j);
; #pragma unroll
;     for (int r = 0; r < NR; ++r) { const int row = row0 + r;
;         const float rn = rsqrtf(wave_sum(ssl[r]) * (1.f / DM) + EPS); float s = 0.f;
; #pragma unroll
;         for (int j = 0; j < 4; ++j) { const f32x4 yf = {bflo(yy[r][j].x), bfhi(yy[r][j].x), bflo(yy[r][j].y), bfhi(yy[r][j].y)};
;             v[r][j] = v[r][j] + yf * rn * g[j]; s += (v[r][j][0] * v[r][j][0] + v[r][j][1] * v[r][j][1]) + (v[r][j][2] * v[r][j][2] + v[r][j][3] * v[r][j][3]); }
;         s = wave_sum(s);
;         f32x4* oo = (f32x4*)(out + (size_t)row * DM) + lane; u32x2* o = (u32x2*)(xb + (size_t)row * DM) + lane;
; #pragma unroll
;         for (int j = 0; j < 4; ++j) { if (WOUT) oo[64 * j] = v[r][j]; if (WXB) { u32x2 w; w.x = cvtpk(v[r][j][0], v[r][j][1]); w.y = cvtpk(v[r][j][2], v[r][j][3]); o[64 * j] = w; } }
;         if (WXB && lane == 0) rs[row] = rsqrtf(s * (1.f / DM) + EPS); }
.LBB0_640:
	s_or_b64 exec, exec, s[2:3]
	s_waitcnt vmcnt(0)
	s_add_u32 s2, s8, 3
	v_readlane_b32 s40, v253, 29
	s_addc_u32 s3, s9, 0
	s_add_i32 s12, s8, 0xffff0003
	v_add_f32_dpp v120, v120, v120 quad_perm:[1,0,3,2] row_mask:0xf bank_mask:0xf
	v_readlane_b32 s41, v253, 30
	s_cmp_lt_i32 s8, 0xfffd
	v_readlane_b32 s42, v253, 31
	v_readlane_b32 s43, v253, 32
	s_mov_b64 s[16:17], s[40:41]
	v_add_f32_dpp v120, v120, v120 quad_perm:[2,3,0,1] row_mask:0xf bank_mask:0xf
	s_cselect_b32 s3, s3, 0
	s_cselect_b32 s2, s2, s12
	s_mov_b64 s[18:19], s[42:43]
	s_cselect_b32 s12, s17, s19
	s_cselect_b32 s13, s16, s18
	s_lshl_b64 s[2:3], s[2:3], 12
	s_add_u32 s2, s13, s2
	s_addc_u32 s3, s12, s3
	s_mov_b32 s12, 0xf001000
	v_add_co_u32_e32 v86, vcc, s12, v90
	v_add_f32_dpp v120, v120, v120 row_half_mirror row_mask:0xf bank_mask:0xf
	v_addc_co_u32_e32 v87, vcc, 0, v91, vcc
	global_load_dwordx4 v[30:33], v20, s[2:3]
	global_load_dwordx2 v[94:95], v[86:87], off offset:2048
	global_load_dwordx4 v[26:29], v20, s[2:3] offset:1024
	global_load_dwordx2 v[92:93], v[86:87], off offset:2560
	global_load_dwordx4 v[22:25], v20, s[2:3] offset:2048
	global_load_dwordx2 v[88:89], v[86:87], off offset:3072
	s_nop 0
	global_load_dwordx4 v[18:21], v20, s[2:3] offset:3072
	s_nop 0
	global_load_dwordx2 v[86:87], v[86:87], off offset:3584
	v_and_b32_e32 v131, 0xffff0000, v118
	s_mov_b32 s2, 0x2d000000
	v_readlane_b32 s44, v253, 33
	v_readlane_b32 s45, v253, 34
	v_add_f32_dpp v120, v120, v120 row_mirror row_mask:0xf bank_mask:0xf
	v_mov_b32_e32 v130, v120
	v_mov_b32_e32 v254, v120
	s_nop 1
	v_permlane16_swap_b32_e32 v130, v254
	v_readlane_b32 s46, v253, 35
	v_readlane_b32 s47, v253, 36
	v_readlane_b32 s48, v253, 37
	v_readlane_b32 s49, v253, 38
	v_add_f32_e32 v120, v254, v130
	v_mov_b32_e32 v130, v120
	v_mov_b32_e32 v254, v120
	s_nop 1
	v_permlane32_swap_b32_e32 v130, v254
	v_readlane_b32 s50, v253, 39
	v_readlane_b32 s51, v253, 40
	v_readlane_b32 s52, v253, 41
	v_readlane_b32 s53, v253, 42
	v_add_f32_e32 v120, v254, v130
	v_fmamk_f32 v120, v120, 0x3a800000, v241
	v_cmp_gt_f32_e32 vcc, s21, v120
	v_mul_f32_e32 v130, 0x4b800000, v120
	v_readlane_b32 s54, v253, 43
	v_cndmask_b32_e32 v120, v120, v130, vcc
	v_rsq_f32_e32 v120, v120
	v_readlane_b32 s55, v253, 44
	v_mul_f32_e32 v130, 0x45800000, v120
	v_cndmask_b32_e32 v120, v120, v130, vcc
	v_lshlrev_b32_e32 v130, 16, v118
	v_lshlrev_b32_e32 v118, 16, v119
	v_and_b32_e32 v119, 0xffff0000, v119
	v_pk_mul_f32 v[130:131], v[120:121], v[130:131] op_sel_hi:[0,1]
	v_pk_mul_f32 v[118:119], v[120:121], v[118:119] op_sel_hi:[0,1]
	v_pk_fma_f32 v[80:81], v[4:5], v[118:119], v[80:81]
	v_pk_fma_f32 v[78:79], v[2:3], v[130:131], v[78:79]
	v_mul_f32_e32 v119, v81, v81
	v_mul_f32_e32 v118, v79, v79
	v_fmac_f32_e32 v118, v78, v78
	v_fmac_f32_e32 v119, v80, v80
	v_add_f32_e32 v130, v118, v119
	v_lshlrev_b32_e32 v118, 16, v116
	v_and_b32_e32 v119, 0xffff0000, v116
	v_lshlrev_b32_e32 v116, 16, v117
	v_and_b32_e32 v117, 0xffff0000, v117
	v_pk_mul_f32 v[118:119], v[120:121], v[118:119] op_sel_hi:[0,1]
	v_pk_mul_f32 v[116:117], v[120:121], v[116:117] op_sel_hi:[0,1]
	v_pk_fma_f32 v[76:77], v[8:9], v[116:117], v[76:77]
	v_pk_fma_f32 v[74:75], v[6:7], v[118:119], v[74:75]
	v_mul_f32_e32 v117, v77, v77
	v_mul_f32_e32 v116, v75, v75
	v_fmac_f32_e32 v116, v74, v74
	v_fmac_f32_e32 v117, v76, v76
	v_add_f32_e32 v116, v116, v117
	v_add_f32_e32 v118, v130, v116
	v_lshlrev_b32_e32 v116, 16, v114
	v_and_b32_e32 v117, 0xffff0000, v114
	v_lshlrev_b32_e32 v114, 16, v115
	v_and_b32_e32 v115, 0xffff0000, v115
	v_pk_mul_f32 v[116:117], v[120:121], v[116:117] op_sel_hi:[0,1]
	v_pk_mul_f32 v[114:115], v[120:121], v[114:115] op_sel_hi:[0,1]
	v_pk_fma_f32 v[72:73], v[12:13], v[114:115], v[72:73]
	v_pk_fma_f32 v[70:71], v[10:11], v[116:117], v[70:71]
	v_mul_f32_e32 v115, v73, v73
	v_mul_f32_e32 v114, v71, v71
	v_fmac_f32_e32 v114, v70, v70
	v_fmac_f32_e32 v115, v72, v72
	v_add_f32_e32 v114, v114, v115
	v_add_f32_e32 v116, v114, v118
	v_lshlrev_b32_e32 v114, 16, v112
	v_and_b32_e32 v115, 0xffff0000, v112
	v_lshlrev_b32_e32 v112, 16, v113
	v_and_b32_e32 v113, 0xffff0000, v113
	v_pk_mul_f32 v[114:115], v[120:121], v[114:115] op_sel_hi:[0,1]
	v_pk_mul_f32 v[112:113], v[120:121], v[112:113] op_sel_hi:[0,1]
	v_pk_fma_f32 v[112:113], v[16:17], v[112:113], v[68:69]
	v_pk_fma_f32 v[114:115], v[14:15], v[114:115], v[66:67]
	v_mul_f32_e32 v67, v113, v113
	v_mul_f32_e32 v66, v115, v115
	v_fmac_f32_e32 v66, v114, v114
	v_fmac_f32_e32 v67, v112, v112
	v_add_f32_e32 v66, v66, v67
	v_add_f32_e32 v66, v66, v116
	v_cvt_pk_bf16_f32 v70, v70, v71
	v_cvt_pk_bf16_f32 v71, v72, v73
	v_cvt_pk_bf16_f32 v78, v78, v79
	v_cvt_pk_bf16_f32 v79, v80, v81
	v_add_f32_dpp v66, v66, v66 quad_perm:[1,0,3,2] row_mask:0xf bank_mask:0xf
	v_cvt_pk_bf16_f32 v74, v74, v75
	v_cvt_pk_bf16_f32 v75, v76, v77
	v_add_f32_dpp v66, v66, v66 quad_perm:[2,3,0,1] row_mask:0xf bank_mask:0xf
	s_nop 1
	v_add_f32_dpp v66, v66, v66 row_half_mirror row_mask:0xf bank_mask:0xf
	s_nop 1
	v_add_f32_dpp v66, v66, v66 row_mirror row_mask:0xf bank_mask:0xf
	v_mov_b32_e32 v67, v66
	v_mov_b32_e32 v254, v66
	s_nop 1
	v_permlane16_swap_b32_e32 v67, v254
	v_add_f32_e32 v68, v254, v67
	v_mov_b32_e32 v69, v68
	v_mov_b32_e32 v254, v68
	s_nop 1
	v_permlane32_swap_b32_e32 v69, v254
	v_add_co_u32_e32 v66, vcc, s2, v90
	s_nop 1
	v_addc_co_u32_e32 v67, vcc, 0, v91, vcc
	global_store_dwordx2 v[66:67], v[70:71], off offset:1024
	v_cvt_pk_bf16_f32 v70, v114, v115
	v_cvt_pk_bf16_f32 v71, v112, v113
	global_store_dwordx2 v[66:67], v[78:79], off
	global_store_dwordx2 v[66:67], v[74:75], off offset:512
	global_store_dwordx2 v[66:67], v[70:71], off offset:1536
	s_and_saveexec_b64 s[2:3], s[6:7]
	s_cbranch_execz .LBB0_642
	v_add_f32_e32 v68, v254, v69
	v_fmamk_f32 v68, v68, 0x3a800000, v241
	v_mul_f32_e32 v69, 0x4b800000, v68
	v_cmp_gt_f32_e32 vcc, s21, v68
	s_add_u32 s12, s0, s10
	s_addc_u32 s13, s1, s11
	v_cndmask_b32_e32 v68, v68, v69, vcc
	v_rsq_f32_e32 v68, v68
	s_nop 0
	v_mul_f32_e32 v69, 0x45800000, v68
	v_cndmask_b32_e32 v70, v68, v69, vcc
	v_mov_b32_e32 v68, s12
	v_add_co_u32_e32 v68, vcc, 0x3b750000, v68
	v_mov_b32_e32 v69, s13
	s_nop 0
	v_addc_co_u32_e32 v69, vcc, 0, v69, vcc
	global_store_dword v[68:69], v70, off
; __device__ __forceinline__ unsigned cvtpk(float lo, float hi) { f32x2 v = {lo, hi}; bf16x2_t b = __builtin_convertvector(v, bf16x2_t); return __builtin_bit_cast(unsigned, b); }
; __device__ __forceinline__ float bflo(unsigned u) { return __uint_as_float(u << 16); }
; __device__ __forceinline__ float bfhi(unsigned u) { return __uint_as_float(u & 0xffff0000u); }
; template <int NR, bool XBF, bool WOUT, bool WXB = true>
; __device__ __forceinline__ void rows_final(const float* xp, const float* xs, const bf16_t* __restrict__ Y, const float* __restrict__ ss, const float* __restrict__ gpost, float* out, bf16_t* xb, float* rs, int row0, int lane) {
;     ...
;     for (int r = 0; r < NR; ++r) { const int row = row0 + r;
;         const float rn = rsqrtf(wave_sum(ssl[r]) * (1.f / DM) + EPS); float s = 0.f;
; #pragma unroll
;         for (int j = 0; j < 4; ++j) { const f32x4 yf = {bflo(yy[r][j].x), bfhi(yy[r][j].x), bflo(yy[r][j].y), bfhi(yy[r][j].y)};
;             v[r][j] = v[r][j] + yf * rn * g[j]; s += (v[r][j][0] * v[r][j][0] + v[r][j][1] * v[r][j][1]) + (v[r][j][2] * v[r][j][2] + v[r][j][3] * v[r][j][3]); }
;         s = wave_sum(s);
;         f32x4* oo = (f32x4*)(out + (size_t)row * DM) + lane; u32x2* o = (u32x2*)(xb + (size_t)row * DM) + lane;
; #pragma unroll
;         for (int j = 0; j < 4; ++j) { if (WOUT) oo[64 * j] = v[r][j]; if (WXB) { u32x2 w; w.x = cvtpk(v[r][j][0], v[r][j][1]); w.y = cvtpk(v[r][j][2], v[r][j][3]); o[64 * j] = w; } }
;         if (WXB && lane == 0) rs[row] = rsqrtf(s * (1.f / DM) + EPS); }
.LBB0_642:
	s_or_b64 exec, exec, s[2:3]
	v_lshlrev_b32_e32 v70, 16, v110
	v_and_b32_e32 v71, 0xffff0000, v110
	v_lshlrev_b32_e32 v72, 16, v111
	v_and_b32_e32 v73, 0xffff0000, v111
	v_add_f32_dpp v68, v129, v129 quad_perm:[1,0,3,2] row_mask:0xf bank_mask:0xf
	s_nop 1
	v_add_f32_dpp v68, v68, v68 quad_perm:[2,3,0,1] row_mask:0xf bank_mask:0xf
	s_nop 1
	v_add_f32_dpp v68, v68, v68 row_half_mirror row_mask:0xf bank_mask:0xf
	s_nop 1
	v_add_f32_dpp v68, v68, v68 row_mirror row_mask:0xf bank_mask:0xf
	v_mov_b32_e32 v69, v68
	v_mov_b32_e32 v254, v68
	s_nop 1
	v_permlane16_swap_b32_e32 v69, v254
	v_add_f32_e32 v68, v254, v69
	v_mov_b32_e32 v69, v68
	v_mov_b32_e32 v254, v68
	s_nop 1
	v_permlane32_swap_b32_e32 v69, v254
	v_add_f32_e32 v68, v254, v69
	v_fmamk_f32 v68, v68, 0x3a800000, v241
	v_cmp_gt_f32_e32 vcc, s21, v68
	v_mul_f32_e32 v69, 0x4b800000, v68
	s_nop 0
	v_cndmask_b32_e32 v68, v68, v69, vcc
	v_rsq_f32_e32 v68, v68
	s_nop 0
	v_mul_f32_e32 v69, 0x45800000, v68
	v_cndmask_b32_e32 v68, v68, v69, vcc
	v_pk_mul_f32 v[70:71], v[68:69], v[70:71] op_sel_hi:[0,1]
	v_pk_mul_f32 v[72:73], v[68:69], v[72:73] op_sel_hi:[0,1]
	v_pk_fma_f32 v[64:65], v[4:5], v[72:73], v[64:65]
	v_pk_fma_f32 v[62:63], v[2:3], v[70:71], v[62:63]
	v_mul_f32_e32 v70, v65, v65
	v_mul_f32_e32 v69, v63, v63
	v_fmac_f32_e32 v69, v62, v62
	v_fmac_f32_e32 v70, v64, v64
	v_add_f32_e32 v69, v69, v70
	v_lshlrev_b32_e32 v70, 16, v108
	v_and_b32_e32 v71, 0xffff0000, v108
	v_lshlrev_b32_e32 v72, 16, v109
	v_and_b32_e32 v73, 0xffff0000, v109
	v_pk_mul_f32 v[70:71], v[68:69], v[70:71] op_sel_hi:[0,1]
	v_pk_mul_f32 v[72:73], v[68:69], v[72:73] op_sel_hi:[0,1]
	v_pk_fma_f32 v[60:61], v[8:9], v[72:73], v[60:61]
	v_pk_fma_f32 v[58:59], v[6:7], v[70:71], v[58:59]
	v_mul_f32_e32 v71, v61, v61
	v_mul_f32_e32 v70, v59, v59
	v_fmac_f32_e32 v70, v58, v58
	v_fmac_f32_e32 v71, v60, v60
	v_add_f32_e32 v70, v70, v71
	v_add_f32_e32 v69, v69, v70
	v_lshlrev_b32_e32 v70, 16, v106
	v_and_b32_e32 v71, 0xffff0000, v106
	v_lshlrev_b32_e32 v72, 16, v107
	v_and_b32_e32 v73, 0xffff0000, v107
	v_pk_mul_f32 v[70:71], v[68:69], v[70:71] op_sel_hi:[0,1]
	v_pk_mul_f32 v[72:73], v[68:69], v[72:73] op_sel_hi:[0,1]
	v_pk_fma_f32 v[56:57], v[12:13], v[72:73], v[56:57]
	v_pk_fma_f32 v[54:55], v[10:11], v[70:71], v[54:55]
	v_mul_f32_e32 v71, v57, v57
	v_mul_f32_e32 v70, v55, v55
	v_fmac_f32_e32 v70, v54, v54
	v_fmac_f32_e32 v71, v56, v56
	v_add_f32_e32 v70, v70, v71
	v_add_f32_e32 v74, v70, v69
	v_lshlrev_b32_e32 v70, 16, v104
	v_and_b32_e32 v71, 0xffff0000, v104
	v_lshlrev_b32_e32 v72, 16, v105
	v_and_b32_e32 v73, 0xffff0000, v105
	v_pk_mul_f32 v[70:71], v[68:69], v[70:71] op_sel_hi:[0,1]
	v_pk_mul_f32 v[68:69], v[68:69], v[72:73] op_sel_hi:[0,1]
	v_pk_fma_f32 v[52:53], v[16:17], v[68:69], v[52:53]
	v_pk_fma_f32 v[68:69], v[14:15], v[70:71], v[50:51]
	v_mul_f32_e32 v51, v53, v53
	v_mul_f32_e32 v50, v69, v69
	v_fmac_f32_e32 v50, v68, v68
	v_fmac_f32_e32 v51, v52, v52
	v_add_f32_e32 v50, v50, v51
	v_add_f32_e32 v50, v50, v74
	v_cvt_pk_bf16_f32 v54, v54, v55
	v_cvt_pk_bf16_f32 v55, v56, v57
	v_cvt_pk_bf16_f32 v62, v62, v63
	v_cvt_pk_bf16_f32 v63, v64, v65
	v_add_f32_dpp v50, v50, v50 quad_perm:[1,0,3,2] row_mask:0xf bank_mask:0xf
	v_cvt_pk_bf16_f32 v58, v58, v59
	v_cvt_pk_bf16_f32 v59, v60, v61
	global_store_dwordx2 v[66:67], v[54:55], off offset:3072
	v_cvt_pk_bf16_f32 v54, v68, v69
	v_add_f32_dpp v50, v50, v50 quad_perm:[2,3,0,1] row_mask:0xf bank_mask:0xf
	v_cvt_pk_bf16_f32 v55, v52, v53
	global_store_dwordx2 v[66:67], v[62:63], off offset:2048
	global_store_dwordx2 v[66:67], v[58:59], off offset:2560
	global_store_dwordx2 v[66:67], v[54:55], off offset:3584
	v_add_f32_dpp v50, v50, v50 row_half_mirror row_mask:0xf bank_mask:0xf
	s_nop 1
	v_add_f32_dpp v50, v50, v50 row_mirror row_mask:0xf bank_mask:0xf
	v_mov_b32_e32 v51, v50
	v_mov_b32_e32 v254, v50
	s_nop 1
	v_permlane16_swap_b32_e32 v51, v254
	v_add_f32_e32 v50, v254, v51
	v_mov_b32_e32 v51, v50
	v_mov_b32_e32 v254, v50
	s_nop 1
	v_permlane32_swap_b32_e32 v51, v254
	s_and_saveexec_b64 s[2:3], s[6:7]
	s_cbranch_execz .LBB0_644
	v_add_f32_e32 v50, v254, v51
	v_fmamk_f32 v50, v50, 0x3a800000, v241
	v_mul_f32_e32 v51, 0x4b800000, v50
	v_cmp_gt_f32_e32 vcc, s21, v50
	s_add_u32 s12, s0, s10
	s_addc_u32 s13, s1, s11
	v_cndmask_b32_e32 v50, v50, v51, vcc
	v_rsq_f32_e32 v50, v50
	s_nop 0
	v_mul_f32_e32 v51, 0x45800000, v50
	v_cndmask_b32_e32 v52, v50, v51, vcc
	v_mov_b32_e32 v50, s12
	v_add_co_u32_e32 v50, vcc, 0x3b750000, v50
	v_mov_b32_e32 v51, s13
	s_nop 0
	v_addc_co_u32_e32 v51, vcc, 0, v51, vcc
	global_store_dword v[50:51], v52, off offset:4
; __device__ __forceinline__ unsigned cvtpk(float lo, float hi) { f32x2 v = {lo, hi}; bf16x2_t b = __builtin_convertvector(v, bf16x2_t); return __builtin_bit_cast(unsigned, b); }
; __device__ __forceinline__ float bflo(unsigned u) { return __uint_as_float(u << 16); }
; __device__ __forceinline__ float bfhi(unsigned u) { return __uint_as_float(u & 0xffff0000u); }
; template <int NR, bool XBF, bool WOUT, bool WXB = true>
; __device__ __forceinline__ void rows_final(const float* xp, const float* xs, const bf16_t* __restrict__ Y, const float* __restrict__ ss, const float* __restrict__ gpost, float* out, bf16_t* xb, float* rs, int row0, int lane) {
;     ...
;     for (int r = 0; r < NR; ++r) { const int row = row0 + r;
;         const float rn = rsqrtf(wave_sum(ssl[r]) * (1.f / DM) + EPS); float s = 0.f;
; #pragma unroll
;         for (int j = 0; j < 4; ++j) { const f32x4 yf = {bflo(yy[r][j].x), bfhi(yy[r][j].x), bflo(yy[r][j].y), bfhi(yy[r][j].y)};
;             v[r][j] = v[r][j] + yf * rn * g[j]; s += (v[r][j][0] * v[r][j][0] + v[r][j][1] * v[r][j][1]) + (v[r][j][2] * v[r][j][2] + v[r][j][3] * v[r][j][3]); }
;         s = wave_sum(s);
;         f32x4* oo = (f32x4*)(out + (size_t)row * DM) + lane; u32x2* o = (u32x2*)(xb + (size_t)row * DM) + lane;
; #pragma unroll
;         for (int j = 0; j < 4; ++j) { if (WOUT) oo[64 * j] = v[r][j]; if (WXB) { u32x2 w; w.x = cvtpk(v[r][j][0], v[r][j][1]); w.y = cvtpk(v[r][j][2], v[r][j][3]); o[64 * j] = w; } }
;         if (WXB && lane == 0) rs[row] = rsqrtf(s * (1.f / DM) + EPS); }
.LBB0_644:
	s_or_b64 exec, exec, s[2:3]
	v_lshlrev_b32_e32 v52, 16, v102
	v_and_b32_e32 v53, 0xffff0000, v102
	v_lshlrev_b32_e32 v54, 16, v103
	v_and_b32_e32 v55, 0xffff0000, v103
	v_add_f32_dpp v50, v128, v128 quad_perm:[1,0,3,2] row_mask:0xf bank_mask:0xf
	s_mov_b32 s2, 0x2d001000
	s_nop 1
	v_add_f32_dpp v50, v50, v50 quad_perm:[2,3,0,1] row_mask:0xf bank_mask:0xf
	s_nop 1
	v_add_f32_dpp v50, v50, v50 row_half_mirror row_mask:0xf bank_mask:0xf
	s_nop 1
	v_add_f32_dpp v50, v50, v50 row_mirror row_mask:0xf bank_mask:0xf
	v_mov_b32_e32 v51, v50
	v_mov_b32_e32 v254, v50
	s_nop 1
	v_permlane16_swap_b32_e32 v51, v254
	v_add_f32_e32 v50, v254, v51
	v_mov_b32_e32 v51, v50
	v_mov_b32_e32 v254, v50
	s_nop 1
	v_permlane32_swap_b32_e32 v51, v254
	v_add_f32_e32 v50, v254, v51
	v_fmamk_f32 v50, v50, 0x3a800000, v241
	v_cmp_gt_f32_e32 vcc, s21, v50
	v_mul_f32_e32 v51, 0x4b800000, v50
	s_nop 0
	v_cndmask_b32_e32 v50, v50, v51, vcc
	v_rsq_f32_e32 v50, v50
	s_nop 0
	v_mul_f32_e32 v51, 0x45800000, v50
	v_cndmask_b32_e32 v50, v50, v51, vcc
	v_pk_mul_f32 v[52:53], v[50:51], v[52:53] op_sel_hi:[0,1]
	v_pk_mul_f32 v[54:55], v[50:51], v[54:55] op_sel_hi:[0,1]
	v_pk_fma_f32 v[48:49], v[4:5], v[54:55], v[48:49]
	v_pk_fma_f32 v[46:47], v[2:3], v[52:53], v[46:47]
	v_mul_f32_e32 v52, v49, v49
	v_mul_f32_e32 v51, v47, v47
	v_fmac_f32_e32 v51, v46, v46
	v_fmac_f32_e32 v52, v48, v48
	v_add_f32_e32 v51, v51, v52
	v_lshlrev_b32_e32 v52, 16, v100
	v_and_b32_e32 v53, 0xffff0000, v100
	v_lshlrev_b32_e32 v54, 16, v101
	v_and_b32_e32 v55, 0xffff0000, v101
	v_pk_mul_f32 v[52:53], v[50:51], v[52:53] op_sel_hi:[0,1]
	v_pk_mul_f32 v[54:55], v[50:51], v[54:55] op_sel_hi:[0,1]
	v_pk_fma_f32 v[44:45], v[8:9], v[54:55], v[44:45]
	v_pk_fma_f32 v[42:43], v[6:7], v[52:53], v[42:43]
	v_mul_f32_e32 v53, v45, v45
	v_mul_f32_e32 v52, v43, v43
	v_fmac_f32_e32 v52, v42, v42
	v_fmac_f32_e32 v53, v44, v44
	v_add_f32_e32 v52, v52, v53
	v_add_f32_e32 v51, v51, v52
	v_lshlrev_b32_e32 v52, 16, v98
	v_and_b32_e32 v53, 0xffff0000, v98
	v_lshlrev_b32_e32 v54, 16, v99
	v_and_b32_e32 v55, 0xffff0000, v99
	v_pk_mul_f32 v[52:53], v[50:51], v[52:53] op_sel_hi:[0,1]
	v_pk_mul_f32 v[54:55], v[50:51], v[54:55] op_sel_hi:[0,1]
	v_pk_fma_f32 v[40:41], v[12:13], v[54:55], v[40:41]
	v_pk_fma_f32 v[38:39], v[10:11], v[52:53], v[38:39]
	v_mul_f32_e32 v53, v41, v41
	v_mul_f32_e32 v52, v39, v39
	v_fmac_f32_e32 v52, v38, v38
	v_fmac_f32_e32 v53, v40, v40
	v_add_f32_e32 v52, v52, v53
	v_add_f32_e32 v56, v52, v51
	v_lshlrev_b32_e32 v52, 16, v96
	v_and_b32_e32 v53, 0xffff0000, v96
	v_lshlrev_b32_e32 v54, 16, v97
	v_and_b32_e32 v55, 0xffff0000, v97
	v_pk_mul_f32 v[52:53], v[50:51], v[52:53] op_sel_hi:[0,1]
	v_pk_mul_f32 v[50:51], v[50:51], v[54:55] op_sel_hi:[0,1]
	v_pk_fma_f32 v[50:51], v[16:17], v[50:51], v[36:37]
	v_pk_fma_f32 v[52:53], v[14:15], v[52:53], v[34:35]
	v_mul_f32_e32 v35, v51, v51
	v_mul_f32_e32 v34, v53, v53
	v_fmac_f32_e32 v34, v52, v52
	v_fmac_f32_e32 v35, v50, v50
	v_add_f32_e32 v34, v34, v35
	v_add_f32_e32 v34, v34, v56
	v_cvt_pk_bf16_f32 v38, v38, v39
	v_cvt_pk_bf16_f32 v39, v40, v41
	v_cvt_pk_bf16_f32 v46, v46, v47
	v_cvt_pk_bf16_f32 v47, v48, v49
	v_add_f32_dpp v34, v34, v34 quad_perm:[1,0,3,2] row_mask:0xf bank_mask:0xf
	v_cvt_pk_bf16_f32 v42, v42, v43
	v_cvt_pk_bf16_f32 v43, v44, v45
	v_add_f32_dpp v34, v34, v34 quad_perm:[2,3,0,1] row_mask:0xf bank_mask:0xf
	s_nop 1
	v_add_f32_dpp v34, v34, v34 row_half_mirror row_mask:0xf bank_mask:0xf
	s_nop 1
	v_add_f32_dpp v34, v34, v34 row_mirror row_mask:0xf bank_mask:0xf
	v_mov_b32_e32 v35, v34
	v_mov_b32_e32 v254, v34
	s_nop 1
	v_permlane16_swap_b32_e32 v35, v254
	v_add_f32_e32 v36, v254, v35
	v_mov_b32_e32 v37, v36
	v_mov_b32_e32 v254, v36
	s_nop 1
	v_permlane32_swap_b32_e32 v37, v254
	v_add_co_u32_e32 v34, vcc, s2, v90
	s_nop 1
	v_addc_co_u32_e32 v35, vcc, 0, v91, vcc
	global_store_dwordx2 v[34:35], v[38:39], off offset:1024
	v_cvt_pk_bf16_f32 v38, v52, v53
	v_cvt_pk_bf16_f32 v39, v50, v51
	global_store_dwordx2 v[34:35], v[46:47], off
	global_store_dwordx2 v[34:35], v[42:43], off offset:512
	global_store_dwordx2 v[34:35], v[38:39], off offset:1536
	s_and_saveexec_b64 s[2:3], s[6:7]
	s_cbranch_execz .LBB0_646
	v_add_f32_e32 v36, v254, v37
	v_fmamk_f32 v36, v36, 0x3a800000, v241
	v_mul_f32_e32 v37, 0x4b800000, v36
	v_cmp_gt_f32_e32 vcc, s21, v36
	s_add_u32 s12, s0, s10
	s_addc_u32 s13, s1, s11
	v_cndmask_b32_e32 v36, v36, v37, vcc
	v_rsq_f32_e32 v36, v36
	s_nop 0
	v_mul_f32_e32 v37, 0x45800000, v36
	v_cndmask_b32_e32 v38, v36, v37, vcc
	v_mov_b32_e32 v36, s12
	v_add_co_u32_e32 v36, vcc, 0x3b750000, v36
	v_mov_b32_e32 v37, s13
	s_nop 0
	v_addc_co_u32_e32 v37, vcc, 0, v37, vcc
	global_store_dword v[36:37], v38, off offset:8
; __device__ __forceinline__ unsigned cvtpk(float lo, float hi) { f32x2 v = {lo, hi}; bf16x2_t b = __builtin_convertvector(v, bf16x2_t); return __builtin_bit_cast(unsigned, b); }
; __device__ __forceinline__ float bflo(unsigned u) { return __uint_as_float(u << 16); }
; __device__ __forceinline__ float bfhi(unsigned u) { return __uint_as_float(u & 0xffff0000u); }
; template <int NR, bool XBF, bool WOUT, bool WXB = true>
; __device__ __forceinline__ void rows_final(const float* xp, const float* xs, const bf16_t* __restrict__ Y, const float* __restrict__ ss, const float* __restrict__ gpost, float* out, bf16_t* xb, float* rs, int row0, int lane) {
;     ...
;     for (int r = 0; r < NR; ++r) { const int row = row0 + r;
;         const float rn = rsqrtf(wave_sum(ssl[r]) * (1.f / DM) + EPS); float s = 0.f;
; #pragma unroll
;         for (int j = 0; j < 4; ++j) { const f32x4 yf = {bflo(yy[r][j].x), bfhi(yy[r][j].x), bflo(yy[r][j].y), bfhi(yy[r][j].y)};
;             v[r][j] = v[r][j] + yf * rn * g[j]; s += (v[r][j][0] * v[r][j][0] + v[r][j][1] * v[r][j][1]) + (v[r][j][2] * v[r][j][2] + v[r][j][3] * v[r][j][3]); }
;         s = wave_sum(s);
;         f32x4* oo = (f32x4*)(out + (size_t)row * DM) + lane; u32x2* o = (u32x2*)(xb + (size_t)row * DM) + lane;
; #pragma unroll
;         for (int j = 0; j < 4; ++j) { if (WOUT) oo[64 * j] = v[r][j]; if (WXB) { u32x2 w; w.x = cvtpk(v[r][j][0], v[r][j][1]); w.y = cvtpk(v[r][j][2], v[r][j][3]); o[64 * j] = w; } }
;         if (WXB && lane == 0) rs[row] = rsqrtf(s * (1.f / DM) + EPS); }
.LBB0_646:
	s_or_b64 exec, exec, s[2:3]
	s_waitcnt vmcnt(0)
	v_lshlrev_b32_e32 v38, 16, v94
	v_and_b32_e32 v39, 0xffff0000, v94
	v_lshlrev_b32_e32 v40, 16, v95
	v_and_b32_e32 v41, 0xffff0000, v95
	v_add_f32_dpp v36, v127, v127 quad_perm:[1,0,3,2] row_mask:0xf bank_mask:0xf
	s_nop 1
	v_add_f32_dpp v36, v36, v36 quad_perm:[2,3,0,1] row_mask:0xf bank_mask:0xf
	s_nop 1
	v_add_f32_dpp v36, v36, v36 row_half_mirror row_mask:0xf bank_mask:0xf
	s_nop 1
	v_add_f32_dpp v36, v36, v36 row_mirror row_mask:0xf bank_mask:0xf
	v_mov_b32_e32 v37, v36
	v_mov_b32_e32 v254, v36
	s_nop 1
	v_permlane16_swap_b32_e32 v37, v254
	v_add_f32_e32 v36, v254, v37
	v_mov_b32_e32 v37, v36
	v_mov_b32_e32 v254, v36
	s_nop 1
	v_permlane32_swap_b32_e32 v37, v254
	v_add_f32_e32 v36, v254, v37
	v_fmamk_f32 v36, v36, 0x3a800000, v241
	v_cmp_gt_f32_e32 vcc, s21, v36
	v_mul_f32_e32 v37, 0x4b800000, v36
	s_nop 0
	v_cndmask_b32_e32 v36, v36, v37, vcc
	v_rsq_f32_e32 v36, v36
	s_nop 0
	v_mul_f32_e32 v37, 0x45800000, v36
	v_cndmask_b32_e32 v36, v36, v37, vcc
	v_pk_mul_f32 v[38:39], v[36:37], v[38:39] op_sel_hi:[0,1]
	v_pk_mul_f32 v[40:41], v[36:37], v[40:41] op_sel_hi:[0,1]
	v_pk_fma_f32 v[32:33], v[4:5], v[40:41], v[32:33]
	v_pk_fma_f32 v[30:31], v[2:3], v[38:39], v[30:31]
	v_mul_f32_e32 v38, v33, v33
	v_mul_f32_e32 v37, v31, v31
	v_fmac_f32_e32 v37, v30, v30
	v_fmac_f32_e32 v38, v32, v32
	v_add_f32_e32 v37, v37, v38
	v_lshlrev_b32_e32 v38, 16, v92
	v_and_b32_e32 v39, 0xffff0000, v92
	v_lshlrev_b32_e32 v40, 16, v93
	v_and_b32_e32 v41, 0xffff0000, v93
	v_pk_mul_f32 v[38:39], v[36:37], v[38:39] op_sel_hi:[0,1]
	v_pk_mul_f32 v[40:41], v[36:37], v[40:41] op_sel_hi:[0,1]
	v_pk_fma_f32 v[28:29], v[8:9], v[40:41], v[28:29]
	v_pk_fma_f32 v[26:27], v[6:7], v[38:39], v[26:27]
	v_mul_f32_e32 v39, v29, v29
	v_mul_f32_e32 v38, v27, v27
	v_fmac_f32_e32 v38, v26, v26
	v_fmac_f32_e32 v39, v28, v28
	v_add_f32_e32 v38, v38, v39
	v_add_f32_e32 v37, v37, v38
	v_lshlrev_b32_e32 v38, 16, v88
	v_and_b32_e32 v39, 0xffff0000, v88
	v_lshlrev_b32_e32 v40, 16, v89
	v_and_b32_e32 v41, 0xffff0000, v89
	v_pk_mul_f32 v[38:39], v[36:37], v[38:39] op_sel_hi:[0,1]
	v_pk_mul_f32 v[40:41], v[36:37], v[40:41] op_sel_hi:[0,1]
	v_pk_fma_f32 v[24:25], v[12:13], v[40:41], v[24:25]
	v_pk_fma_f32 v[22:23], v[10:11], v[38:39], v[22:23]
	v_mul_f32_e32 v39, v25, v25
	v_mul_f32_e32 v38, v23, v23
	v_fmac_f32_e32 v38, v22, v22
	v_fmac_f32_e32 v39, v24, v24
	v_add_f32_e32 v38, v38, v39
	v_add_f32_e32 v42, v38, v37
	v_lshlrev_b32_e32 v38, 16, v86
	v_and_b32_e32 v39, 0xffff0000, v86
	v_lshlrev_b32_e32 v40, 16, v87
	v_and_b32_e32 v41, 0xffff0000, v87
	v_pk_mul_f32 v[38:39], v[36:37], v[38:39] op_sel_hi:[0,1]
	v_pk_mul_f32 v[36:37], v[36:37], v[40:41] op_sel_hi:[0,1]
	v_pk_fma_f32 v[20:21], v[16:17], v[36:37], v[20:21]
	v_pk_fma_f32 v[36:37], v[14:15], v[38:39], v[18:19]
	v_mul_f32_e32 v19, v21, v21
	v_mul_f32_e32 v18, v37, v37
	v_fmac_f32_e32 v18, v36, v36
	v_fmac_f32_e32 v19, v20, v20
	v_add_f32_e32 v18, v18, v19
	v_add_f32_e32 v18, v18, v42
	v_cvt_pk_bf16_f32 v22, v22, v23
	v_cvt_pk_bf16_f32 v23, v24, v25
	v_cvt_pk_bf16_f32 v30, v30, v31
	v_cvt_pk_bf16_f32 v31, v32, v33
	v_add_f32_dpp v18, v18, v18 quad_perm:[1,0,3,2] row_mask:0xf bank_mask:0xf
	v_cvt_pk_bf16_f32 v26, v26, v27
	v_cvt_pk_bf16_f32 v27, v28, v29
	global_store_dwordx2 v[34:35], v[22:23], off offset:3072
	v_cvt_pk_bf16_f32 v22, v36, v37
	v_add_f32_dpp v18, v18, v18 quad_perm:[2,3,0,1] row_mask:0xf bank_mask:0xf
	v_cvt_pk_bf16_f32 v23, v20, v21
	global_store_dwordx2 v[34:35], v[30:31], off offset:2048
	global_store_dwordx2 v[34:35], v[26:27], off offset:2560
	global_store_dwordx2 v[34:35], v[22:23], off offset:3584
	v_add_f32_dpp v18, v18, v18 row_half_mirror row_mask:0xf bank_mask:0xf
	s_nop 1
	v_add_f32_dpp v18, v18, v18 row_mirror row_mask:0xf bank_mask:0xf
	v_mov_b32_e32 v19, v18
	v_mov_b32_e32 v254, v18
	s_nop 1
	v_permlane16_swap_b32_e32 v19, v254
	v_add_f32_e32 v18, v254, v19
	v_mov_b32_e32 v19, v18
	v_mov_b32_e32 v254, v18
	s_nop 1
	v_permlane32_swap_b32_e32 v19, v254
	s_and_saveexec_b64 s[2:3], s[6:7]
	s_cbranch_execz .LBB0_631
	v_add_f32_e32 v18, v254, v19
	v_fmamk_f32 v18, v18, 0x3a800000, v241
	v_mul_f32_e32 v19, 0x4b800000, v18
	v_cmp_gt_f32_e32 vcc, s21, v18
	s_add_u32 s12, s0, s10
	s_addc_u32 s13, s1, s11
	v_cndmask_b32_e32 v18, v18, v19, vcc
	v_rsq_f32_e32 v18, v18
	s_nop 0
	v_mul_f32_e32 v19, 0x45800000, v18
	v_cndmask_b32_e32 v20, v18, v19, vcc
	v_mov_b32_e32 v18, s12
	v_add_co_u32_e32 v18, vcc, 0x3b750000, v18
	v_mov_b32_e32 v19, s13
	s_nop 0
	v_addc_co_u32_e32 v19, vcc, 0, v19, vcc
	global_store_dword v[18:19], v20, off offset:12
	s_branch .LBB0_631

; __device__ __forceinline__ unsigned cvtpk(float lo, float hi) { f32x2 v = {lo, hi}; bf16x2_t b = __builtin_convertvector(v, bf16x2_t); return __builtin_bit_cast(unsigned, b); }
; __device__ __forceinline__ float bflo(unsigned u) { return __uint_as_float(u << 16); }
; __device__ __forceinline__ float bfhi(unsigned u) { return __uint_as_float(u & 0xffff0000u); }
; template <int NR, bool XBF, bool WOUT, bool WXB = true>
; __device__ __forceinline__ void rows_final(const float* xp, const float* xs, const bf16_t* __restrict__ Y, const float* __restrict__ ss, const float* __restrict__ gpost, float* out, bf16_t* xb, float* rs, int row0, int lane) {
;     f32x4 v[NR][4]; u32x2 yy[NR][4]; float ssl[NR];
; #pragma unroll
;     for (int r = 0; r < NR; ++r) { const int row = row0 + r;
;         const float* xrow = (row < NP_TOK) ? xp + (size_t)row * DM : xs + (size_t)(row - NP_TOK) * DM;
;         ssl[r] = (lane < 32) ? ss[(size_t)row * 32 + lane] : 0.f;
; #pragma unroll
;         for (int j = 0; j < 4; ++j) {
;             if (XBF) { const u32x2 xw = *((const u32x2*)(xb + (size_t)row * DM) + lane + 64 * j); v[r][j] = (f32x4){bflo(xw.x), bfhi(xw.x), bflo(xw.y), bfhi(xw.y)}; }
;             else v[r][j] = *((const f32x4*)xrow + lane + 64 * j);
;             yy[r][j] = *((const u32x2*)(Y + (size_t)row * DM) + lane + 64 * j); } }
;     f32x4 g[4];
; #pragma unroll
;     for (int j = 0; j < 4; ++j) g[j] = *((const f32x4*)gpost + lane + 64 * j);
; #pragma unroll
;     for (int r = 0; r < NR; ++r) { const int row = row0 + r;
;         const float rn = rsqrtf(wave_sum(ssl[r]) * (1.f / DM) + EPS); float s = 0.f;
; #pragma unroll
;         for (int j = 0; j < 4; ++j) { const f32x4 yf = {bflo(yy[r][j].x), bfhi(yy[r][j].x), bflo(yy[r][j].y), bfhi(yy[r][j].y)};
;             v[r][j] = v[r][j] + yf * rn * g[j]; s += (v[r][j][0] * v[r][j][0] + v[r][j][1] * v[r][j][1]) + (v[r][j][2] * v[r][j][2] + v[r][j][3] * v[r][j][3]); }
;         s = wave_sum(s);
;         f32x4* oo = (f32x4*)(out + (size_t)row * DM) + lane; u32x2* o = (u32x2*)(xb + (size_t)row * DM) + lane;
; #pragma unroll
;         for (int j = 0; j < 4; ++j) { if (WOUT) oo[64 * j] = v[r][j]; if (WXB) { u32x2 w; w.x = cvtpk(v[r][j][0], v[r][j][1]); w.y = cvtpk(v[r][j][2], v[r][j][3]); o[64 * j] = w; } }
;         if (WXB && lane == 0) rs[row] = rsqrtf(s * (1.f / DM) + EPS); }
.LBB0_852:
	s_or_b64 exec, exec, s[8:9]
	s_mov_b32 s7, 0x2d001000
	v_add_co_u32_e32 v34, vcc, s7, v40
	s_waitcnt vmcnt(0)
	v_lshlrev_b32_e32 v126, 16, v46
	v_addc_co_u32_e32 v35, vcc, 0, v41, vcc
	global_load_dwordx2 v[78:79], v[34:35], off offset:2048
	global_load_dwordx2 v[80:81], v[34:35], off offset:2560
	global_load_dwordx2 v[112:113], v[34:35], off offset:3072
	global_load_dwordx2 v[114:115], v[34:35], off offset:3584
	v_and_b32_e32 v127, 0xffff0000, v46
	v_lshlrev_b32_e32 v128, 16, v47
	v_and_b32_e32 v129, 0xffff0000, v47
	s_nop 1
	v_mov_b32_dpp v47, v37 quad_perm:[1,0,3,2] row_mask:0xf bank_mask:0xf
	s_nop 1
	v_mov_b32_dpp v46, v36 quad_perm:[1,0,3,2] row_mask:0xf bank_mask:0xf
	v_lshlrev_b32_e32 v130, 16, v42
	v_and_b32_e32 v131, 0xffff0000, v42
	v_lshlrev_b32_e32 v132, 16, v43
	v_and_b32_e32 v133, 0xffff0000, v43
	v_pk_add_f32 v[36:37], v[36:37], v[46:47]
	s_nop 1
	v_mov_b32_dpp v43, v37 quad_perm:[2,3,0,1] row_mask:0xf bank_mask:0xf
	s_nop 1
	v_mov_b32_dpp v42, v36 quad_perm:[2,3,0,1] row_mask:0xf bank_mask:0xf
	v_lshlrev_b32_e32 v136, 16, v86
	v_and_b32_e32 v137, 0xffff0000, v86
	v_lshlrev_b32_e32 v138, 16, v87
	v_and_b32_e32 v139, 0xffff0000, v87
	v_pk_add_f32 v[134:135], v[36:37], v[42:43]
	s_mov_b32 s7, 0x1e001000
	v_lshlrev_b32_e32 v94, 16, v70
	v_and_b32_e32 v95, 0xffff0000, v70
	v_add_co_u32_e32 v70, vcc, s7, v40
	s_mov_b32 s8, 0x358637bd
	v_lshlrev_b32_e32 v96, 16, v71
	v_and_b32_e32 v97, 0xffff0000, v71
	v_addc_co_u32_e32 v71, vcc, 0, v41, vcc
	v_lshlrev_b32_e32 v140, 16, v84
	v_and_b32_e32 v141, 0xffff0000, v84
	v_lshlrev_b32_e32 v90, 16, v74
	v_and_b32_e32 v91, 0xffff0000, v74
	v_lshlrev_b32_e32 v92, 16, v75
	v_and_b32_e32 v93, 0xffff0000, v75
	v_lshlrev_b32_e32 v98, 16, v64
	v_and_b32_e32 v99, 0xffff0000, v64
	v_lshlrev_b32_e32 v100, 16, v65
	v_and_b32_e32 v101, 0xffff0000, v65
	v_lshlrev_b32_e32 v102, 16, v60
	v_and_b32_e32 v103, 0xffff0000, v60
	v_lshlrev_b32_e32 v124, 16, v61
	v_and_b32_e32 v125, 0xffff0000, v61
	v_lshlrev_b32_e32 v120, 16, v54
	v_and_b32_e32 v121, 0xffff0000, v54
	v_lshlrev_b32_e32 v122, 16, v55
	v_and_b32_e32 v123, 0xffff0000, v55
	v_lshlrev_b32_e32 v116, 16, v52
	v_and_b32_e32 v117, 0xffff0000, v52
	v_lshlrev_b32_e32 v118, 16, v53
	v_and_b32_e32 v119, 0xffff0000, v53
	v_lshlrev_b32_e32 v142, 16, v82
	v_and_b32_e32 v143, 0xffff0000, v82
	v_lshlrev_b32_e32 v82, 16, v83
	v_and_b32_e32 v83, 0xffff0000, v83
	s_movk_i32 s7, 0x1000
	v_lshlrev_b32_e32 v44, 16, v48
	v_and_b32_e32 v45, 0xffff0000, v48
	v_lshlrev_b32_e32 v48, 16, v49
	v_and_b32_e32 v49, 0xffff0000, v49
	v_lshlrev_b32_e32 v66, 16, v68
	v_and_b32_e32 v67, 0xffff0000, v68
	v_lshlrev_b32_e32 v68, 16, v69
	v_and_b32_e32 v69, 0xffff0000, v69
	v_lshlrev_b32_e32 v34, 16, v38
	v_and_b32_e32 v35, 0xffff0000, v38
	v_lshlrev_b32_e32 v56, 16, v58
	v_and_b32_e32 v57, 0xffff0000, v58
	v_lshlrev_b32_e32 v38, 16, v39
	v_and_b32_e32 v39, 0xffff0000, v39
	v_lshlrev_b32_e32 v58, 16, v59
	v_and_b32_e32 v59, 0xffff0000, v59
	s_waitcnt vmcnt(0)
	v_lshlrev_b32_e32 v60, 16, v78
	v_and_b32_e32 v61, 0xffff0000, v78
	v_lshlrev_b32_e32 v42, 16, v112
	v_and_b32_e32 v43, 0xffff0000, v112
	v_lshlrev_b32_e32 v46, 16, v113
	v_and_b32_e32 v47, 0xffff0000, v113
	s_nop 1
	v_mov_b32_dpp v113, v135 row_half_mirror row_mask:0xf bank_mask:0xf
	s_nop 1
	v_mov_b32_dpp v112, v134 row_half_mirror row_mask:0xf bank_mask:0xf
	v_lshlrev_b32_e32 v64, 16, v79
	v_and_b32_e32 v65, 0xffff0000, v79
	v_lshlrev_b32_e32 v52, 16, v80
	v_and_b32_e32 v53, 0xffff0000, v80
	v_pk_add_f32 v[112:113], v[134:135], v[112:113]
	s_nop 1
	v_mov_b32_dpp v135, v113 row_mirror row_mask:0xf bank_mask:0xf
	s_nop 1
	v_mov_b32_dpp v134, v112 row_mirror row_mask:0xf bank_mask:0xf
	v_lshlrev_b32_e32 v54, 16, v81
	v_and_b32_e32 v55, 0xffff0000, v81
	global_load_dwordx2 v[80:81], v[70:71], off offset:2048
	global_load_dwordx2 v[78:79], v[70:71], off offset:2560
	global_load_dwordx2 v[74:75], v[70:71], off offset:3072
	s_nop 0
	global_load_dwordx2 v[70:71], v[70:71], off offset:3584
	v_lshlrev_b32_e32 v36, 16, v114
	v_pk_add_f32 v[112:113], v[112:113], v[134:135]
	v_mov_b32_e32 v135, v113
	v_mov_b32_e32 v255, v113
	s_nop 1
	v_permlane16_swap_b32_e32 v135, v255
	v_mov_b32_e32 v134, v112
	v_mov_b32_e32 v254, v112
	s_nop 1
	v_permlane16_swap_b32_e32 v134, v254
	v_and_b32_e32 v37, 0xffff0000, v114
	v_lshlrev_b32_e32 v40, 16, v115
	v_and_b32_e32 v41, 0xffff0000, v115
	v_lshlrev_b32_e32 v114, 16, v88
	v_pk_add_f32 v[86:87], v[254:255], v[134:135]
	v_mov_b32_e32 v113, v87
	v_mov_b32_e32 v255, v87
	s_nop 1
	v_permlane32_swap_b32_e32 v113, v255
	v_mov_b32_e32 v112, v86
	v_mov_b32_e32 v254, v86
	s_nop 1
	v_permlane32_swap_b32_e32 v112, v254
	v_lshlrev_b32_e32 v134, 16, v85
	v_and_b32_e32 v135, 0xffff0000, v85
	v_mov_b64_e32 v[84:85], s[8:9]
	s_mov_b32 s8, 0x3a800000
	v_pk_add_f32 v[86:87], v[254:255], v[112:113]
	v_and_b32_e32 v115, 0xffff0000, v88
	v_pk_fma_f32 v[144:145], v[86:87], s[8:9], v[84:85] op_sel_hi:[1,0,0]
	v_lshlrev_b32_e32 v88, 16, v89
	v_mul_f32_e32 v0, 0x4b800000, v145
	v_cmp_gt_f32_e32 vcc, s21, v145
	v_and_b32_e32 v89, 0xffff0000, v89
	s_nop 0
	v_cndmask_b32_e32 v0, v145, v0, vcc
	v_rsq_f32_e32 v0, v0
	s_nop 0
	v_mul_f32_e32 v86, 0x45800000, v0
	v_cndmask_b32_e32 v0, v0, v86, vcc
	v_pk_mul_f32 v[112:113], v[0:1], v[136:137] op_sel_hi:[0,1]
	v_pk_mul_f32 v[86:87], v[0:1], v[114:115] op_sel_hi:[0,1]
	v_pk_mul_f32 v[114:115], v[0:1], v[138:139] op_sel_hi:[0,1]
	v_pk_fma_f32 v[112:113], v[6:7], v[112:113], v[126:127]
	v_pk_mul_f32 v[126:127], v[0:1], v[140:141] op_sel_hi:[0,1]
	v_pk_mul_f32 v[88:89], v[0:1], v[88:89] op_sel_hi:[0,1]
	v_pk_fma_f32 v[114:115], v[8:9], v[114:115], v[128:129]
; __device__ __forceinline__ unsigned cvtpk(float lo, float hi) { f32x2 v = {lo, hi}; bf16x2_t b = __builtin_convertvector(v, bf16x2_t); return __builtin_bit_cast(unsigned, b); }
; __device__ __forceinline__ float bflo(unsigned u) { return __uint_as_float(u << 16); }
; __device__ __forceinline__ float bfhi(unsigned u) { return __uint_as_float(u & 0xffff0000u); }
; template <int NR, bool XBF, bool WOUT, bool WXB = true>
; __device__ __forceinline__ void rows_final(const float* xp, const float* xs, const bf16_t* __restrict__ Y, const float* __restrict__ ss, const float* __restrict__ gpost, float* out, bf16_t* xb, float* rs, int row0, int lane) {
;     ...
;     for (int r = 0; r < NR; ++r) { const int row = row0 + r;
;         const float rn = rsqrtf(wave_sum(ssl[r]) * (1.f / DM) + EPS); float s = 0.f;
; #pragma unroll
;         for (int j = 0; j < 4; ++j) { const f32x4 yf = {bflo(yy[r][j].x), bfhi(yy[r][j].x), bflo(yy[r][j].y), bfhi(yy[r][j].y)};
;             v[r][j] = v[r][j] + yf * rn * g[j]; s += (v[r][j][0] * v[r][j][0] + v[r][j][1] * v[r][j][1]) + (v[r][j][2] * v[r][j][2] + v[r][j][3] * v[r][j][3]); }
;         s = wave_sum(s);
;         f32x4* oo = (f32x4*)(out + (size_t)row * DM) + lane; u32x2* o = (u32x2*)(xb + (size_t)row * DM) + lane;
; #pragma unroll
;         for (int j = 0; j < 4; ++j) { if (WOUT) oo[64 * j] = v[r][j]; if (WXB) { u32x2 w; w.x = cvtpk(v[r][j][0], v[r][j][1]); w.y = cvtpk(v[r][j][2], v[r][j][3]); o[64 * j] = w; } }
	v_pk_mul_f32 v[128:129], v[0:1], v[134:135] op_sel_hi:[0,1]
	v_pk_fma_f32 v[116:117], v[10:11], v[126:127], v[116:117]
	v_pk_mul_f32 v[126:127], v[0:1], v[142:143] op_sel_hi:[0,1]
	v_pk_mul_f32 v[82:83], v[0:1], v[82:83] op_sel_hi:[0,1]
	v_mul_f32_e32 v0, 0x4b800000, v144
	v_cmp_gt_f32_e32 vcc, s21, v144
	v_pk_fma_f32 v[122:123], v[16:17], v[82:83], v[122:123]
	v_and_b32_e32 v83, 0xffff0000, v76
	v_cndmask_b32_e32 v0, v144, v0, vcc
	v_rsq_f32_e32 v0, v0
	v_pk_fma_f32 v[88:89], v[4:5], v[88:89], v[132:133]
	v_pk_fma_f32 v[86:87], v[2:3], v[86:87], v[130:131]
	global_store_dwordx4 v[20:21], v[86:89], off
	v_mul_f32_e32 v82, 0x45800000, v0
	v_cndmask_b32_e32 v0, v0, v82, vcc
	v_lshlrev_b32_e32 v82, 16, v76
	v_lshlrev_b32_e32 v76, 16, v77
	v_and_b32_e32 v77, 0xffff0000, v77
	v_pk_mul_f32 v[76:77], v[0:1], v[76:77] op_sel_hi:[0,1]
	v_pk_fma_f32 v[88:89], v[4:5], v[76:77], v[124:125]
	v_lshlrev_b32_e32 v76, 16, v72
	v_and_b32_e32 v77, 0xffff0000, v72
	v_lshlrev_b32_e32 v72, 16, v73
	v_and_b32_e32 v73, 0xffff0000, v73
	v_pk_mul_f32 v[72:73], v[0:1], v[72:73] op_sel_hi:[0,1]
	v_pk_fma_f32 v[100:101], v[8:9], v[72:73], v[100:101]
	v_lshlrev_b32_e32 v72, 16, v62
	v_and_b32_e32 v73, 0xffff0000, v62
	v_lshlrev_b32_e32 v62, 16, v63
	v_and_b32_e32 v63, 0xffff0000, v63
	v_pk_mul_f32 v[62:63], v[0:1], v[62:63] op_sel_hi:[0,1]
	v_pk_fma_f32 v[96:97], v[12:13], v[62:63], v[96:97]
	v_lshlrev_b32_e32 v62, 16, v50
	v_and_b32_e32 v63, 0xffff0000, v50
	v_lshlrev_b32_e32 v50, 16, v51
	v_and_b32_e32 v51, 0xffff0000, v51
	v_pk_mul_f32 v[50:51], v[0:1], v[50:51] op_sel_hi:[0,1]
	v_pk_fma_f32 v[92:93], v[16:17], v[50:51], v[92:93]
	s_nop 1
	v_mov_b32_dpp v51, v27 quad_perm:[1,0,3,2] row_mask:0xf bank_mask:0xf
	s_nop 1
	v_mov_b32_dpp v50, v26 quad_perm:[1,0,3,2] row_mask:0xf bank_mask:0xf
	v_pk_mul_f32 v[62:63], v[0:1], v[62:63] op_sel_hi:[0,1]
	v_pk_fma_f32 v[90:91], v[14:15], v[62:63], v[90:91]
	v_add_co_u32_e32 v62, vcc, s7, v20
	v_pk_add_f32 v[26:27], v[26:27], v[50:51]
	s_nop 1
	v_mov_b32_dpp v51, v27 quad_perm:[2,3,0,1] row_mask:0xf bank_mask:0xf
	s_nop 1
	v_mov_b32_dpp v50, v26 quad_perm:[2,3,0,1] row_mask:0xf bank_mask:0xf
	v_pk_mul_f32 v[72:73], v[0:1], v[72:73] op_sel_hi:[0,1]
	v_addc_co_u32_e32 v63, vcc, 0, v21, vcc
	s_movk_i32 s7, 0x2000
	v_pk_add_f32 v[26:27], v[26:27], v[50:51]
	s_nop 1
	v_mov_b32_dpp v51, v27 row_half_mirror row_mask:0xf bank_mask:0xf
	s_nop 1
	v_mov_b32_dpp v50, v26 row_half_mirror row_mask:0xf bank_mask:0xf
	v_pk_fma_f32 v[94:95], v[10:11], v[72:73], v[94:95]
	v_add_co_u32_e32 v72, vcc, s7, v20
	v_pk_mul_f32 v[82:83], v[0:1], v[82:83] op_sel_hi:[0,1]
	v_pk_add_f32 v[26:27], v[26:27], v[50:51]
	s_nop 1
	v_mov_b32_dpp v51, v27 row_mirror row_mask:0xf bank_mask:0xf
	s_nop 1
	v_mov_b32_dpp v50, v26 row_mirror row_mask:0xf bank_mask:0xf
	v_addc_co_u32_e32 v73, vcc, 0, v21, vcc
	v_pk_mul_f32 v[76:77], v[0:1], v[76:77] op_sel_hi:[0,1]
	v_pk_fma_f32 v[86:87], v[2:3], v[82:83], v[102:103]
	v_pk_add_f32 v[26:27], v[26:27], v[50:51]
	v_mov_b32_e32 v51, v27
	v_mov_b32_e32 v255, v27
	s_nop 1
	v_permlane16_swap_b32_e32 v51, v255
	v_mov_b32_e32 v50, v26
	v_mov_b32_e32 v254, v26
	s_nop 1
	v_permlane16_swap_b32_e32 v50, v254
	v_pk_fma_f32 v[118:119], v[12:13], v[128:129], v[118:119]
	v_pk_fma_f32 v[120:121], v[14:15], v[126:127], v[120:121]
	global_store_dwordx4 v[20:21], v[112:115], off offset:1024
	global_store_dwordx4 v[20:21], v[116:119], off offset:2048
	global_store_dwordx4 v[20:21], v[120:123], off offset:3072
	v_pk_fma_f32 v[98:99], v[6:7], v[76:77], v[98:99]
	v_pk_add_f32 v[26:27], v[254:255], v[50:51]
	v_mov_b32_e32 v51, v27
	v_mov_b32_e32 v255, v27
	s_nop 1
	v_permlane32_swap_b32_e32 v51, v255
	v_mov_b32_e32 v50, v26
	v_mov_b32_e32 v254, v26
	s_nop 1
	v_permlane32_swap_b32_e32 v50, v254
	global_store_dwordx4 v[72:73], v[86:89], off offset:-4096
	global_store_dwordx4 v[62:63], v[98:101], off offset:1024
	global_store_dwordx4 v[62:63], v[94:97], off offset:2048
	global_store_dwordx4 v[62:63], v[90:93], off offset:3072
	v_lshlrev_b32_e32 v88, 16, v24
	v_and_b32_e32 v89, 0xffff0000, v24
	v_pk_add_f32 v[26:27], v[254:255], v[50:51]
	v_lshlrev_b32_e32 v62, 16, v32
	v_pk_fma_f32 v[84:85], v[26:27], s[8:9], v[84:85] op_sel_hi:[1,0,0]
	v_and_b32_e32 v63, 0xffff0000, v32
	v_mul_f32_e32 v0, 0x4b800000, v85
	v_cmp_gt_f32_e32 vcc, s21, v85
	v_lshlrev_b32_e32 v32, 16, v33
	v_and_b32_e32 v33, 0xffff0000, v33
	v_cndmask_b32_e32 v0, v85, v0, vcc
	v_rsq_f32_e32 v0, v0
	v_lshlrev_b32_e32 v82, 16, v28
	v_and_b32_e32 v83, 0xffff0000, v28
	v_lshlrev_b32_e32 v86, 16, v29
	v_mul_f32_e32 v24, 0x45800000, v0
	v_and_b32_e32 v87, 0xffff0000, v29
	v_cndmask_b32_e32 v0, v0, v24, vcc
	v_lshlrev_b32_e32 v76, 16, v30
	v_and_b32_e32 v77, 0xffff0000, v30
	v_lshlrev_b32_e32 v30, 16, v31
	v_and_b32_e32 v31, 0xffff0000, v31
	v_lshlrev_b32_e32 v90, 16, v25
	v_and_b32_e32 v91, 0xffff0000, v25
	v_pk_mul_f32 v[26:27], v[0:1], v[32:33] op_sel_hi:[0,1]
	v_pk_mul_f32 v[32:33], v[0:1], v[82:83] op_sel_hi:[0,1]
	v_pk_mul_f32 v[50:51], v[0:1], v[86:87] op_sel_hi:[0,1]
	v_pk_mul_f32 v[24:25], v[0:1], v[62:63] op_sel_hi:[0,1]
	v_pk_mul_f32 v[28:29], v[0:1], v[76:77] op_sel_hi:[0,1]
	v_pk_mul_f32 v[30:31], v[0:1], v[30:31] op_sel_hi:[0,1]
	v_pk_fma_f32 v[50:51], v[12:13], v[50:51], v[48:49]
	v_pk_fma_f32 v[48:49], v[10:11], v[32:33], v[44:45]
	v_pk_mul_f32 v[32:33], v[0:1], v[88:89] op_sel_hi:[0,1]
	v_pk_mul_f32 v[44:45], v[0:1], v[90:91] op_sel_hi:[0,1]
	v_mul_f32_e32 v0, 0x4b800000, v84
	v_cmp_gt_f32_e32 vcc, s21, v84
	v_pk_fma_f32 v[26:27], v[4:5], v[26:27], v[68:69]
	v_pk_fma_f32 v[24:25], v[2:3], v[24:25], v[66:67]
	v_cndmask_b32_e32 v0, v84, v0, vcc
	v_rsq_f32_e32 v0, v0
	global_store_dwordx4 v[72:73], v[24:27], off
	v_readlane_b32 s8, v252, 40
	v_pk_fma_f32 v[28:29], v[6:7], v[28:29], v[56:57]
	v_mul_f32_e32 v24, 0x45800000, v0
	v_pk_fma_f32 v[56:57], v[14:15], v[32:33], v[34:35]
	v_cndmask_b32_e32 v0, v0, v24, vcc
	s_waitcnt vmcnt(0)
; __device__ __forceinline__ unsigned cvtpk(float lo, float hi) { f32x2 v = {lo, hi}; bf16x2_t b = __builtin_convertvector(v, bf16x2_t); return __builtin_bit_cast(unsigned, b); }
; __device__ __forceinline__ float bflo(unsigned u) { return __uint_as_float(u << 16); }
; __device__ __forceinline__ float bfhi(unsigned u) { return __uint_as_float(u & 0xffff0000u); }
; template <int NR, bool XBF, bool WOUT, bool WXB = true>
; __device__ __forceinline__ void rows_final(const float* xp, const float* xs, const bf16_t* __restrict__ Y, const float* __restrict__ ss, const float* __restrict__ gpost, float* out, bf16_t* xb, float* rs, int row0, int lane) {
;     ...
;     for (int r = 0; r < NR; ++r) { const int row = row0 + r;
;         const float rn = rsqrtf(wave_sum(ssl[r]) * (1.f / DM) + EPS); float s = 0.f;
; #pragma unroll
;         for (int j = 0; j < 4; ++j) { const f32x4 yf = {bflo(yy[r][j].x), bfhi(yy[r][j].x), bflo(yy[r][j].y), bfhi(yy[r][j].y)};
;             v[r][j] = v[r][j] + yf * rn * g[j]; s += (v[r][j][0] * v[r][j][0] + v[r][j][1] * v[r][j][1]) + (v[r][j][2] * v[r][j][2] + v[r][j][3] * v[r][j][3]); }
;         s = wave_sum(s);
;         f32x4* oo = (f32x4*)(out + (size_t)row * DM) + lane; u32x2* o = (u32x2*)(xb + (size_t)row * DM) + lane;
; #pragma unroll
;         for (int j = 0; j < 4; ++j) { if (WOUT) oo[64 * j] = v[r][j]; if (WXB) { u32x2 w; w.x = cvtpk(v[r][j][0], v[r][j][1]); w.y = cvtpk(v[r][j][2], v[r][j][3]); o[64 * j] = w; } }
	v_lshlrev_b32_e32 v32, 16, v74
	v_and_b32_e32 v33, 0xffff0000, v74
	v_readlane_b32 s9, v252, 41
	v_pk_mul_f32 v[32:33], v[0:1], v[32:33] op_sel_hi:[0,1]
	s_add_i32 s6, s6, s8
	v_readlane_b32 s8, v252, 34
	v_pk_fma_f32 v[30:31], v[8:9], v[30:31], v[58:59]
	v_pk_fma_f32 v[58:59], v[16:17], v[44:45], v[38:39]
	v_pk_fma_f32 v[32:33], v[10:11], v[32:33], v[42:43]
	v_lshlrev_b32_e32 v38, 16, v70
	v_and_b32_e32 v39, 0xffff0000, v70
	v_lshlrev_b32_e32 v42, 16, v71
	v_and_b32_e32 v43, 0xffff0000, v71
	v_readlane_b32 s9, v252, 35
	v_pk_mul_f32 v[44:45], v[0:1], v[38:39] op_sel_hi:[0,1]
	v_pk_mul_f32 v[38:39], v[0:1], v[42:43] op_sel_hi:[0,1]
	s_movk_i32 s7, 0x3000
	v_lshl_add_u64 v[18:19], v[18:19], 0, s[8:9]
	v_readlane_b32 s8, v252, 42
	v_pk_fma_f32 v[38:39], v[16:17], v[38:39], v[40:41]
	v_add_co_u32_e32 v40, vcc, s7, v20
	v_readlane_b32 s9, v252, 43
	v_lshlrev_b32_e32 v24, 16, v80
	v_and_b32_e32 v25, 0xffff0000, v80
	v_lshlrev_b32_e32 v26, 16, v81
	v_and_b32_e32 v27, 0xffff0000, v81
	v_addc_co_u32_e32 v41, vcc, 0, v21, vcc
	v_lshl_add_u64 v[20:21], v[20:21], 0, s[8:9]
	v_readlane_b32 s8, v252, 38
	global_store_dwordx4 v[72:73], v[28:31], off offset:1024
	global_store_dwordx4 v[72:73], v[48:51], off offset:2048
	global_store_dwordx4 v[72:73], v[56:59], off offset:3072
	v_pk_mul_f32 v[24:25], v[0:1], v[24:25] op_sel_hi:[0,1]
	v_pk_mul_f32 v[26:27], v[0:1], v[26:27] op_sel_hi:[0,1]
	v_lshlrev_b32_e32 v28, 16, v78
	v_and_b32_e32 v29, 0xffff0000, v78
	v_lshlrev_b32_e32 v30, 16, v79
	v_and_b32_e32 v31, 0xffff0000, v79
	v_lshlrev_b32_e32 v34, 16, v75
	v_and_b32_e32 v35, 0xffff0000, v75
	v_readlane_b32 s9, v252, 39
	v_pk_fma_f32 v[26:27], v[4:5], v[26:27], v[64:65]
	v_pk_fma_f32 v[24:25], v[2:3], v[24:25], v[60:61]
	v_pk_mul_f32 v[28:29], v[0:1], v[28:29] op_sel_hi:[0,1]
	v_pk_mul_f32 v[30:31], v[0:1], v[30:31] op_sel_hi:[0,1]
	v_pk_mul_f32 v[34:35], v[0:1], v[34:35] op_sel_hi:[0,1]
	s_cmp_lt_i32 s6, 0x14000
	v_lshl_add_u64 v[22:23], v[22:23], 0, s[8:9]
	v_pk_fma_f32 v[30:31], v[8:9], v[30:31], v[54:55]
	v_pk_fma_f32 v[28:29], v[6:7], v[28:29], v[52:53]
	v_pk_fma_f32 v[34:35], v[12:13], v[34:35], v[46:47]
	v_pk_fma_f32 v[36:37], v[14:15], v[44:45], v[36:37]
	global_store_dwordx4 v[40:41], v[24:27], off
	global_store_dwordx4 v[40:41], v[28:31], off offset:1024
	global_store_dwordx4 v[40:41], v[32:35], off offset:2048
	global_store_dwordx4 v[40:41], v[36:39], off offset:3072
	s_cbranch_scc0 .LBB0_861

; __device__ __forceinline__ float bflo(unsigned u) { return __uint_as_float(u << 16); }
; __device__ __forceinline__ float bfhi(unsigned u) { return __uint_as_float(u & 0xffff0000u); }
; template <int NR, bool XBF, bool WOUT, bool WXB = true>
; __device__ __forceinline__ void rows_final(const float* xp, const float* xs, const bf16_t* __restrict__ Y, const float* __restrict__ ss, const float* __restrict__ gpost, float* out, bf16_t* xb, float* rs, int row0, int lane) {
;     ...
;     for (int r = 0; r < NR; ++r) { const int row = row0 + r;
;         const float* xrow = (row < NP_TOK) ? xp + (size_t)row * DM : xs + (size_t)(row - NP_TOK) * DM;
;         ssl[r] = (lane < 32) ? ss[(size_t)row * 32 + lane] : 0.f;
; #pragma unroll
;         for (int j = 0; j < 4; ++j) {
;             if (XBF) { const u32x2 xw = *((const u32x2*)(xb + (size_t)row * DM) + lane + 64 * j); v[r][j] = (f32x4){bflo(xw.x), bfhi(xw.x), bflo(xw.y), bfhi(xw.y)}; }
;             else v[r][j] = *((const f32x4*)xrow + lane + 64 * j);
;             yy[r][j] = *((const u32x2*)(Y + (size_t)row * DM) + lane + 64 * j); } }
.LBB0_866:
	v_mov_b32_e32 v87, 0
	v_lshl_add_u64 v[30:31], s[0:1], 0, v[18:19]
	v_mov_b32_e32 v34, 0
	s_and_saveexec_b64 s[10:11], s[2:3]
	s_cbranch_execz .LBB0_868
	v_add_co_u32_e32 v22, vcc, 0x3c1a0000, v30
	s_nop 0
	v_addc_co_u32_e32 v23, vcc, 0, v31, vcc
	global_load_dword v34, v[22:23], off
.LBB0_868:
	s_or_b64 exec, exec, s[10:11]
	v_lshl_add_u64 v[22:23], s[0:1], 0, v[20:21]
	v_add_co_u32_e32 v24, vcc, 0x2d000000, v22
	s_nop 1
	v_addc_co_u32_e32 v25, vcc, 0, v23, vcc
	v_add_co_u32_e32 v36, vcc, 0x1e000000, v22
	s_nop 1
	v_addc_co_u32_e32 v37, vcc, 0, v23, vcc
	global_load_dwordx2 v[32:33], v[24:25], off
	global_load_dwordx2 v[28:29], v[24:25], off offset:512
	global_load_dwordx2 v[26:27], v[24:25], off offset:1024
	s_nop 0
	global_load_dwordx2 v[24:25], v[24:25], off offset:1536
	s_nop 0
	global_load_dwordx2 v[78:79], v[36:37], off
	global_load_dwordx2 v[76:77], v[36:37], off offset:512
	global_load_dwordx2 v[74:75], v[36:37], off offset:1024
	global_load_dwordx2 v[72:73], v[36:37], off offset:1536
	s_and_saveexec_b64 s[10:11], s[2:3]
	s_cbranch_execz .LBB0_870
	v_add_co_u32_e32 v36, vcc, 0x3c1a0000, v30
	s_nop 1
	v_addc_co_u32_e32 v37, vcc, 0, v31, vcc
	global_load_dword v87, v[36:37], off offset:128

; __device__ __forceinline__ unsigned cvtpk(float lo, float hi) { f32x2 v = {lo, hi}; bf16x2_t b = __builtin_convertvector(v, bf16x2_t); return __builtin_bit_cast(unsigned, b); }
; __device__ __forceinline__ float bflo(unsigned u) { return __uint_as_float(u << 16); }
; __device__ __forceinline__ float bfhi(unsigned u) { return __uint_as_float(u & 0xffff0000u); }
; template <int NR, bool XBF, bool WOUT, bool WXB = true>
; __device__ __forceinline__ void rows_final(const float* xp, const float* xs, const bf16_t* __restrict__ Y, const float* __restrict__ ss, const float* __restrict__ gpost, float* out, bf16_t* xb, float* rs, int row0, int lane) {
;     ...
;     for (int r = 0; r < NR; ++r) { const int row = row0 + r;
;         const float rn = rsqrtf(wave_sum(ssl[r]) * (1.f / DM) + EPS); float s = 0.f;
; #pragma unroll
;         for (int j = 0; j < 4; ++j) { const f32x4 yf = {bflo(yy[r][j].x), bfhi(yy[r][j].x), bflo(yy[r][j].y), bfhi(yy[r][j].y)};
;             v[r][j] = v[r][j] + yf * rn * g[j]; s += (v[r][j][0] * v[r][j][0] + v[r][j][1] * v[r][j][1]) + (v[r][j][2] * v[r][j][2] + v[r][j][3] * v[r][j][3]); }
;         s = wave_sum(s);
;         f32x4* oo = (f32x4*)(out + (size_t)row * DM) + lane; u32x2* o = (u32x2*)(xb + (size_t)row * DM) + lane;
; #pragma unroll
;         for (int j = 0; j < 4; ++j) { if (WOUT) oo[64 * j] = v[r][j]; if (WXB) { u32x2 w; w.x = cvtpk(v[r][j][0], v[r][j][1]); w.y = cvtpk(v[r][j][2], v[r][j][3]); o[64 * j] = w; } }
;         if (WXB && lane == 0) rs[row] = rsqrtf(s * (1.f / DM) + EPS); }
.LBB0_874:
	s_or_b64 exec, exec, s[10:11]
	s_waitcnt vmcnt(0)
	v_lshlrev_b32_e32 v92, 16, v28
	v_and_b32_e32 v93, 0xffff0000, v28
	v_lshlrev_b32_e32 v94, 16, v29
	v_and_b32_e32 v95, 0xffff0000, v29
	v_add_f32_dpp v28, v34, v34 quad_perm:[1,0,3,2] row_mask:0xf bank_mask:0xf
	v_lshlrev_b32_e32 v96, 16, v26
	v_and_b32_e32 v97, 0xffff0000, v26
	v_lshlrev_b32_e32 v98, 16, v27
	v_and_b32_e32 v99, 0xffff0000, v27
	v_add_f32_dpp v26, v28, v28 quad_perm:[2,3,0,1] row_mask:0xf bank_mask:0xf
	s_mov_b32 s7, 0x2d001000
	v_lshlrev_b32_e32 v100, 16, v24
	v_and_b32_e32 v101, 0xffff0000, v24
	v_add_co_u32_e32 v24, vcc, s7, v22
	v_add_f32_dpp v26, v26, v26 row_half_mirror row_mask:0xf bank_mask:0xf
	v_lshlrev_b32_e32 v102, 16, v25
	v_and_b32_e32 v103, 0xffff0000, v25
	v_addc_co_u32_e32 v25, vcc, 0, v23, vcc
	v_add_f32_dpp v26, v26, v26 row_mirror row_mask:0xf bank_mask:0xf
	v_mov_b32_e32 v27, v26
	v_mov_b32_e32 v254, v26
	s_nop 1
	v_permlane16_swap_b32_e32 v27, v254
	s_mov_b32 s7, 0x1e001000
	v_lshlrev_b32_e32 v88, 16, v32
	v_and_b32_e32 v89, 0xffff0000, v32
	v_lshlrev_b32_e32 v90, 16, v33
	v_add_f32_e32 v26, v254, v27
	v_mov_b32_e32 v27, v26
	v_mov_b32_e32 v254, v26
	s_nop 1
	v_permlane32_swap_b32_e32 v27, v254
	v_and_b32_e32 v91, 0xffff0000, v33
	v_add_co_u32_e32 v104, vcc, s7, v22
	global_load_dwordx2 v[38:39], v[24:25], off offset:2048
	global_load_dwordx2 v[36:37], v[24:25], off offset:2560
	global_load_dwordx2 v[34:35], v[24:25], off offset:3072
	global_load_dwordx2 v[32:33], v[24:25], off offset:3584
	v_add_f32_e32 v24, v254, v27
	v_addc_co_u32_e32 v105, vcc, 0, v23, vcc
	v_fmamk_f32 v24, v24, 0x3a800000, v241
	v_mul_f32_e32 v25, 0x4b800000, v24
	v_cmp_gt_f32_e32 vcc, s21, v24
	v_and_b32_e32 v107, 0xffff0000, v78
	s_mov_b64 s[10:11], 0x2d000000
	v_cndmask_b32_e32 v24, v24, v25, vcc
	v_rsq_f32_e32 v106, v24
	global_load_dwordx2 v[30:31], v[104:105], off offset:2048
	global_load_dwordx2 v[28:29], v[104:105], off offset:2560
	global_load_dwordx2 v[26:27], v[104:105], off offset:3072
	global_load_dwordx2 v[24:25], v[104:105], off offset:3584
	v_mul_f32_e32 v104, 0x45800000, v106
	v_cndmask_b32_e32 v104, v106, v104, vcc
	v_lshlrev_b32_e32 v106, 16, v78
	v_lshlrev_b32_e32 v78, 16, v79
	v_and_b32_e32 v79, 0xffff0000, v79
	v_pk_mul_f32 v[106:107], v[104:105], v[106:107] op_sel_hi:[0,1]
	v_pk_mul_f32 v[78:79], v[104:105], v[78:79] op_sel_hi:[0,1]
	v_pk_fma_f32 v[78:79], v[4:5], v[78:79], v[90:91]
	v_pk_fma_f32 v[88:89], v[2:3], v[106:107], v[88:89]
	v_mul_f32_e32 v91, v79, v79
	v_mul_f32_e32 v90, v89, v89
	v_fmac_f32_e32 v90, v88, v88
	v_fmac_f32_e32 v91, v78, v78
	v_add_f32_e32 v105, v90, v91
	v_lshlrev_b32_e32 v90, 16, v76
	v_and_b32_e32 v91, 0xffff0000, v76
	v_lshlrev_b32_e32 v76, 16, v77
	v_and_b32_e32 v77, 0xffff0000, v77
	v_pk_mul_f32 v[90:91], v[104:105], v[90:91] op_sel_hi:[0,1]
	v_pk_mul_f32 v[76:77], v[104:105], v[76:77] op_sel_hi:[0,1]
	v_pk_fma_f32 v[76:77], v[8:9], v[76:77], v[94:95]
	v_pk_fma_f32 v[90:91], v[6:7], v[90:91], v[92:93]
	v_mul_f32_e32 v93, v77, v77
	v_mul_f32_e32 v92, v91, v91
	v_fmac_f32_e32 v92, v90, v90
	v_fmac_f32_e32 v93, v76, v76
	v_add_f32_e32 v92, v92, v93
	v_add_f32_e32 v94, v105, v92
	v_lshlrev_b32_e32 v92, 16, v74
	v_and_b32_e32 v93, 0xffff0000, v74
	v_lshlrev_b32_e32 v74, 16, v75
	v_and_b32_e32 v75, 0xffff0000, v75
	v_pk_mul_f32 v[92:93], v[104:105], v[92:93] op_sel_hi:[0,1]
	v_pk_mul_f32 v[74:75], v[104:105], v[74:75] op_sel_hi:[0,1]
	v_pk_fma_f32 v[74:75], v[12:13], v[74:75], v[98:99]
	v_pk_fma_f32 v[92:93], v[10:11], v[92:93], v[96:97]
	v_mul_f32_e32 v96, v75, v75
	v_mul_f32_e32 v95, v93, v93
	v_fmac_f32_e32 v95, v92, v92
	v_fmac_f32_e32 v96, v74, v74
	v_add_f32_e32 v95, v95, v96
	v_add_f32_e32 v98, v95, v94
	v_lshlrev_b32_e32 v94, 16, v72
	v_and_b32_e32 v95, 0xffff0000, v72
	v_lshlrev_b32_e32 v72, 16, v73
	v_and_b32_e32 v73, 0xffff0000, v73
	v_pk_mul_f32 v[94:95], v[104:105], v[94:95] op_sel_hi:[0,1]
	v_pk_mul_f32 v[72:73], v[104:105], v[72:73] op_sel_hi:[0,1]
	v_pk_fma_f32 v[96:97], v[16:17], v[72:73], v[102:103]
	v_pk_fma_f32 v[94:95], v[14:15], v[94:95], v[100:101]
	v_mul_f32_e32 v73, v97, v97
	v_mul_f32_e32 v72, v95, v95
	v_fmac_f32_e32 v72, v94, v94
	v_fmac_f32_e32 v73, v96, v96
	v_add_f32_e32 v72, v72, v73
	v_add_f32_e32 v72, v72, v98
	v_lshl_add_u64 v[98:99], v[22:23], 0, s[10:11]
	s_mov_b64 s[10:11], 0x2d000200
	v_lshl_add_u64 v[100:101], v[22:23], 0, s[10:11]
	s_mov_b64 s[10:11], 0x2d000400
	v_add_f32_dpp v72, v72, v72 quad_perm:[1,0,3,2] row_mask:0xf bank_mask:0xf
	v_lshl_add_u64 v[102:103], v[22:23], 0, s[10:11]
	s_mov_b64 s[10:11], 0x2d000600
	v_lshl_add_u64 v[104:105], v[22:23], 0, s[10:11]
	v_cvt_pk_bf16_f32 v88, v88, v89
	v_add_f32_dpp v72, v72, v72 quad_perm:[2,3,0,1] row_mask:0xf bank_mask:0xf
	v_cvt_pk_bf16_f32 v89, v78, v79
	v_cvt_pk_bf16_f32 v78, v90, v91
	v_cvt_pk_bf16_f32 v79, v76, v77
	v_cvt_pk_bf16_f32 v76, v92, v93
	v_add_f32_dpp v72, v72, v72 row_half_mirror row_mask:0xf bank_mask:0xf
	v_cvt_pk_bf16_f32 v77, v74, v75
	v_cvt_pk_bf16_f32 v74, v94, v95
	v_cvt_pk_bf16_f32 v75, v96, v97
	global_store_dwordx2 v[98:99], v[88:89], off
	v_add_f32_dpp v72, v72, v72 row_mirror row_mask:0xf bank_mask:0xf
	v_mov_b32_e32 v73, v72
	v_mov_b32_e32 v254, v72
	s_nop 1
	v_permlane16_swap_b32_e32 v73, v254
	global_store_dwordx2 v[100:101], v[78:79], off
	global_store_dwordx2 v[102:103], v[76:77], off
	global_store_dwordx2 v[104:105], v[74:75], off
	v_add_f32_e32 v72, v254, v73
	v_mov_b32_e32 v73, v72
	v_mov_b32_e32 v254, v72
	s_nop 1
	v_permlane32_swap_b32_e32 v73, v254
	s_and_saveexec_b64 s[10:11], s[4:5]
	s_cbranch_execz .LBB0_876
	v_add_f32_e32 v72, v254, v73
	v_fmamk_f32 v72, v72, 0x3a800000, v241
	v_mul_f32_e32 v73, 0x4b800000, v72
	v_cmp_gt_f32_e32 vcc, s21, v72
	s_add_u32 s7, s0, s8
	s_addc_u32 s12, s1, s9
	v_cndmask_b32_e32 v72, v72, v73, vcc
	v_rsq_f32_e32 v72, v72
	s_nop 0
	v_mul_f32_e32 v73, 0x45800000, v72
	v_cndmask_b32_e32 v74, v72, v73, vcc
	v_mov_b32_e32 v72, s7
	v_add_co_u32_e32 v72, vcc, 0x3b700000, v72
	v_mov_b32_e32 v73, s12
	s_nop 0
	v_addc_co_u32_e32 v73, vcc, 0, v73, vcc
	global_store_dword v[72:73], v74, off
; __device__ __forceinline__ unsigned cvtpk(float lo, float hi) { f32x2 v = {lo, hi}; bf16x2_t b = __builtin_convertvector(v, bf16x2_t); return __builtin_bit_cast(unsigned, b); }
; __device__ __forceinline__ float bflo(unsigned u) { return __uint_as_float(u << 16); }
; __device__ __forceinline__ float bfhi(unsigned u) { return __uint_as_float(u & 0xffff0000u); }
; template <int NR, bool XBF, bool WOUT, bool WXB = true>
; __device__ __forceinline__ void rows_final(const float* xp, const float* xs, const bf16_t* __restrict__ Y, const float* __restrict__ ss, const float* __restrict__ gpost, float* out, bf16_t* xb, float* rs, int row0, int lane) {
;     ...
;     for (int r = 0; r < NR; ++r) { const int row = row0 + r;
;         const float rn = rsqrtf(wave_sum(ssl[r]) * (1.f / DM) + EPS); float s = 0.f;
; #pragma unroll
;         for (int j = 0; j < 4; ++j) { const f32x4 yf = {bflo(yy[r][j].x), bfhi(yy[r][j].x), bflo(yy[r][j].y), bfhi(yy[r][j].y)};
;             v[r][j] = v[r][j] + yf * rn * g[j]; s += (v[r][j][0] * v[r][j][0] + v[r][j][1] * v[r][j][1]) + (v[r][j][2] * v[r][j][2] + v[r][j][3] * v[r][j][3]); }
;         s = wave_sum(s);
;         f32x4* oo = (f32x4*)(out + (size_t)row * DM) + lane; u32x2* o = (u32x2*)(xb + (size_t)row * DM) + lane;
; #pragma unroll
;         for (int j = 0; j < 4; ++j) { if (WOUT) oo[64 * j] = v[r][j]; if (WXB) { u32x2 w; w.x = cvtpk(v[r][j][0], v[r][j][1]); w.y = cvtpk(v[r][j][2], v[r][j][3]); o[64 * j] = w; } }
;         if (WXB && lane == 0) rs[row] = rsqrtf(s * (1.f / DM) + EPS); }
.LBB0_876:
	s_or_b64 exec, exec, s[10:11]
	v_and_b32_e32 v91, 0xffff0000, v60
	v_and_b32_e32 v89, 0xffff0000, v62
	v_and_b32_e32 v73, 0xffff0000, v70
	s_mov_b64 s[10:11], 0x2d000800
	v_add_f32_dpp v74, v87, v87 quad_perm:[1,0,3,2] row_mask:0xf bank_mask:0xf
	v_lshlrev_b32_e32 v72, 16, v70
	v_lshlrev_b32_e32 v70, 16, v71
	v_and_b32_e32 v71, 0xffff0000, v71
	v_add_f32_dpp v76, v74, v74 quad_perm:[2,3,0,1] row_mask:0xf bank_mask:0xf
	v_lshlrev_b32_e32 v74, 16, v68
	v_and_b32_e32 v75, 0xffff0000, v68
	v_lshlrev_b32_e32 v68, 16, v69
	v_and_b32_e32 v69, 0xffff0000, v69
	v_add_f32_dpp v78, v76, v76 row_half_mirror row_mask:0xf bank_mask:0xf
	v_lshlrev_b32_e32 v76, 16, v66
	v_and_b32_e32 v77, 0xffff0000, v66
	v_lshlrev_b32_e32 v66, 16, v67
	v_and_b32_e32 v67, 0xffff0000, v67
	v_add_f32_dpp v87, v78, v78 row_mirror row_mask:0xf bank_mask:0xf
	v_mov_b32_e32 v88, v87
	v_mov_b32_e32 v254, v87
	s_nop 1
	v_permlane16_swap_b32_e32 v88, v254
	v_lshlrev_b32_e32 v78, 16, v64
	v_and_b32_e32 v79, 0xffff0000, v64
	v_lshlrev_b32_e32 v64, 16, v65
	v_and_b32_e32 v65, 0xffff0000, v65
	v_add_f32_e32 v87, v254, v88
	v_mov_b32_e32 v90, v87
	v_mov_b32_e32 v254, v87
	s_nop 1
	v_permlane32_swap_b32_e32 v90, v254
	v_lshlrev_b32_e32 v88, 16, v62
	v_lshlrev_b32_e32 v62, 16, v63
	v_and_b32_e32 v63, 0xffff0000, v63
	v_add_f32_e32 v87, v254, v90
	v_fmamk_f32 v87, v87, 0x3a800000, v241
	v_mul_f32_e32 v90, 0x4b800000, v87
	v_cmp_gt_f32_e32 vcc, s21, v87
	s_nop 1
	v_cndmask_b32_e32 v87, v87, v90, vcc
	v_rsq_f32_e32 v87, v87
	v_lshlrev_b32_e32 v90, 16, v60
	v_mul_f32_e32 v60, 0x45800000, v87
	v_cndmask_b32_e32 v60, v87, v60, vcc
	v_pk_mul_f32 v[88:89], v[60:61], v[88:89] op_sel_hi:[0,1]
	v_pk_mul_f32 v[62:63], v[60:61], v[62:63] op_sel_hi:[0,1]
	v_pk_fma_f32 v[62:63], v[4:5], v[62:63], v[70:71]
	v_pk_fma_f32 v[70:71], v[2:3], v[88:89], v[72:73]
	v_mul_f32_e32 v73, v63, v63
	v_mul_f32_e32 v72, v71, v71
	v_fmac_f32_e32 v72, v70, v70
	v_fmac_f32_e32 v73, v62, v62
	v_add_f32_e32 v87, v72, v73
	v_lshlrev_b32_e32 v72, 16, v61
	v_and_b32_e32 v73, 0xffff0000, v61
	v_pk_mul_f32 v[88:89], v[60:61], v[90:91] op_sel_hi:[0,1]
	v_pk_mul_f32 v[72:73], v[60:61], v[72:73] op_sel_hi:[0,1]
	v_pk_fma_f32 v[68:69], v[8:9], v[72:73], v[68:69]
	v_pk_fma_f32 v[72:73], v[6:7], v[88:89], v[74:75]
	v_mul_f32_e32 v74, v69, v69
	v_mul_f32_e32 v61, v73, v73
	v_fmac_f32_e32 v61, v72, v72
	v_fmac_f32_e32 v74, v68, v68
	v_add_f32_e32 v61, v61, v74
	v_add_f32_e32 v61, v87, v61
	v_lshlrev_b32_e32 v74, 16, v58
	v_and_b32_e32 v75, 0xffff0000, v58
	v_lshlrev_b32_e32 v58, 16, v59
	v_and_b32_e32 v59, 0xffff0000, v59
	v_pk_mul_f32 v[74:75], v[60:61], v[74:75] op_sel_hi:[0,1]
	v_pk_mul_f32 v[58:59], v[60:61], v[58:59] op_sel_hi:[0,1]
	v_pk_fma_f32 v[58:59], v[12:13], v[58:59], v[66:67]
	v_pk_fma_f32 v[66:67], v[10:11], v[74:75], v[76:77]
	v_mul_f32_e32 v75, v59, v59
	v_mul_f32_e32 v74, v67, v67
	v_fmac_f32_e32 v74, v66, v66
	v_fmac_f32_e32 v75, v58, v58
	v_add_f32_e32 v74, v74, v75
	v_add_f32_e32 v76, v74, v61
	v_lshlrev_b32_e32 v74, 16, v56
	v_and_b32_e32 v75, 0xffff0000, v56
	v_lshlrev_b32_e32 v56, 16, v57
	v_and_b32_e32 v57, 0xffff0000, v57
	v_pk_mul_f32 v[74:75], v[60:61], v[74:75] op_sel_hi:[0,1]
	v_pk_mul_f32 v[56:57], v[60:61], v[56:57] op_sel_hi:[0,1]
	v_pk_fma_f32 v[60:61], v[16:17], v[56:57], v[64:65]
	v_pk_fma_f32 v[64:65], v[14:15], v[74:75], v[78:79]
	v_mul_f32_e32 v57, v61, v61
	v_mul_f32_e32 v56, v65, v65
	v_fmac_f32_e32 v56, v64, v64
	v_fmac_f32_e32 v57, v60, v60
	v_add_f32_e32 v56, v56, v57
	v_add_f32_e32 v56, v56, v76
	v_lshl_add_u64 v[74:75], v[22:23], 0, s[10:11]
	s_mov_b64 s[10:11], 0x2d000a00
	v_lshl_add_u64 v[76:77], v[22:23], 0, s[10:11]
	s_mov_b64 s[10:11], 0x2d000c00
	v_add_f32_dpp v56, v56, v56 quad_perm:[1,0,3,2] row_mask:0xf bank_mask:0xf
	v_lshl_add_u64 v[78:79], v[22:23], 0, s[10:11]
	s_mov_b64 s[10:11], 0x2d000e00
	v_cvt_pk_bf16_f32 v70, v70, v71
	v_cvt_pk_bf16_f32 v71, v62, v63
	v_add_f32_dpp v56, v56, v56 quad_perm:[2,3,0,1] row_mask:0xf bank_mask:0xf
	v_cvt_pk_bf16_f32 v62, v72, v73
	v_cvt_pk_bf16_f32 v63, v68, v69
	v_lshl_add_u64 v[88:89], v[22:23], 0, s[10:11]
	global_store_dwordx2 v[76:77], v[62:63], off
	v_add_f32_dpp v56, v56, v56 row_half_mirror row_mask:0xf bank_mask:0xf
	v_cvt_pk_bf16_f32 v62, v66, v67
	v_cvt_pk_bf16_f32 v63, v58, v59
	v_cvt_pk_bf16_f32 v58, v64, v65
	v_cvt_pk_bf16_f32 v59, v60, v61
	v_add_f32_dpp v56, v56, v56 row_mirror row_mask:0xf bank_mask:0xf
	v_mov_b32_e32 v57, v56
	v_mov_b32_e32 v254, v56
	s_nop 1
	v_permlane16_swap_b32_e32 v57, v254
	global_store_dwordx2 v[74:75], v[70:71], off
	global_store_dwordx2 v[78:79], v[62:63], off
	global_store_dwordx2 v[88:89], v[58:59], off
	v_add_f32_e32 v56, v254, v57
	v_mov_b32_e32 v57, v56
	v_mov_b32_e32 v254, v56
	s_nop 1
	v_permlane32_swap_b32_e32 v57, v254
	s_and_saveexec_b64 s[10:11], s[4:5]
	s_cbranch_execz .LBB0_878
	v_add_f32_e32 v56, v254, v57
	v_fmamk_f32 v56, v56, 0x3a800000, v241
	v_mul_f32_e32 v57, 0x4b800000, v56
	v_cmp_gt_f32_e32 vcc, s21, v56
	s_add_u32 s7, s0, s8
	s_addc_u32 s12, s1, s9
	v_cndmask_b32_e32 v56, v56, v57, vcc
	v_rsq_f32_e32 v56, v56
	s_nop 0
	v_mul_f32_e32 v57, 0x45800000, v56
	v_cndmask_b32_e32 v58, v56, v57, vcc
	v_mov_b32_e32 v56, s7
	v_add_co_u32_e32 v56, vcc, 0x3b700000, v56
	v_mov_b32_e32 v57, s12
	s_nop 0
	v_addc_co_u32_e32 v57, vcc, 0, v57, vcc
	global_store_dword v[56:57], v58, off offset:4
; __device__ __forceinline__ unsigned cvtpk(float lo, float hi) { f32x2 v = {lo, hi}; bf16x2_t b = __builtin_convertvector(v, bf16x2_t); return __builtin_bit_cast(unsigned, b); }
; __device__ __forceinline__ float bflo(unsigned u) { return __uint_as_float(u << 16); }
; __device__ __forceinline__ float bfhi(unsigned u) { return __uint_as_float(u & 0xffff0000u); }
; template <int NR, bool XBF, bool WOUT, bool WXB = true>
; __device__ __forceinline__ void rows_final(const float* xp, const float* xs, const bf16_t* __restrict__ Y, const float* __restrict__ ss, const float* __restrict__ gpost, float* out, bf16_t* xb, float* rs, int row0, int lane) {
;     ...
;     for (int r = 0; r < NR; ++r) { const int row = row0 + r;
;         const float rn = rsqrtf(wave_sum(ssl[r]) * (1.f / DM) + EPS); float s = 0.f;
; #pragma unroll
;         for (int j = 0; j < 4; ++j) { const f32x4 yf = {bflo(yy[r][j].x), bfhi(yy[r][j].x), bflo(yy[r][j].y), bfhi(yy[r][j].y)};
;             v[r][j] = v[r][j] + yf * rn * g[j]; s += (v[r][j][0] * v[r][j][0] + v[r][j][1] * v[r][j][1]) + (v[r][j][2] * v[r][j][2] + v[r][j][3] * v[r][j][3]); }
;         s = wave_sum(s);
;         f32x4* oo = (f32x4*)(out + (size_t)row * DM) + lane; u32x2* o = (u32x2*)(xb + (size_t)row * DM) + lane;
; #pragma unroll
;         for (int j = 0; j < 4; ++j) { if (WOUT) oo[64 * j] = v[r][j]; if (WXB) { u32x2 w; w.x = cvtpk(v[r][j][0], v[r][j][1]); w.y = cvtpk(v[r][j][2], v[r][j][3]); o[64 * j] = w; } }
;         if (WXB && lane == 0) rs[row] = rsqrtf(s * (1.f / DM) + EPS); }
.LBB0_878:
	s_or_b64 exec, exec, s[10:11]
	v_and_b32_e32 v57, 0xffff0000, v54
	s_mov_b64 s[10:11], 0x2d001000
	v_add_f32_dpp v58, v86, v86 quad_perm:[1,0,3,2] row_mask:0xf bank_mask:0xf
	v_lshlrev_b32_e32 v56, 16, v54
	v_lshlrev_b32_e32 v54, 16, v55
	v_and_b32_e32 v55, 0xffff0000, v55
	v_add_f32_dpp v60, v58, v58 quad_perm:[2,3,0,1] row_mask:0xf bank_mask:0xf
	v_lshlrev_b32_e32 v58, 16, v52
	v_and_b32_e32 v59, 0xffff0000, v52
	v_lshlrev_b32_e32 v52, 16, v53
	v_and_b32_e32 v53, 0xffff0000, v53
	v_add_f32_dpp v62, v60, v60 row_half_mirror row_mask:0xf bank_mask:0xf
	v_lshlrev_b32_e32 v60, 16, v50
	v_and_b32_e32 v61, 0xffff0000, v50
	v_lshlrev_b32_e32 v50, 16, v51
	v_and_b32_e32 v51, 0xffff0000, v51
	v_add_f32_dpp v64, v62, v62 row_mirror row_mask:0xf bank_mask:0xf
	v_mov_b32_e32 v65, v64
	v_mov_b32_e32 v254, v64
	s_nop 1
	v_permlane16_swap_b32_e32 v65, v254
	v_lshlrev_b32_e32 v62, 16, v48
	v_and_b32_e32 v63, 0xffff0000, v48
	v_lshlrev_b32_e32 v48, 16, v49
	v_and_b32_e32 v49, 0xffff0000, v49
	v_add_f32_e32 v66, v254, v65
	v_mov_b32_e32 v67, v66
	v_mov_b32_e32 v254, v66
	s_nop 1
	v_permlane32_swap_b32_e32 v67, v254
	v_lshlrev_b32_e32 v64, 16, v46
	v_and_b32_e32 v65, 0xffff0000, v46
	v_lshlrev_b32_e32 v46, 16, v47
	v_and_b32_e32 v47, 0xffff0000, v47
	v_add_f32_e32 v66, v254, v67
	v_fmamk_f32 v66, v66, 0x3a800000, v241
	v_mul_f32_e32 v67, 0x4b800000, v66
	v_cmp_gt_f32_e32 vcc, s21, v66
	s_nop 1
	v_cndmask_b32_e32 v66, v66, v67, vcc
	v_rsq_f32_e32 v68, v66
	v_lshlrev_b32_e32 v66, 16, v44
	v_and_b32_e32 v67, 0xffff0000, v44
	v_mul_f32_e32 v44, 0x45800000, v68
	v_cndmask_b32_e32 v44, v68, v44, vcc
	v_pk_mul_f32 v[64:65], v[44:45], v[64:65] op_sel_hi:[0,1]
	v_pk_mul_f32 v[46:47], v[44:45], v[46:47] op_sel_hi:[0,1]
	v_pk_fma_f32 v[46:47], v[4:5], v[46:47], v[54:55]
	v_pk_fma_f32 v[54:55], v[2:3], v[64:65], v[56:57]
	v_mul_f32_e32 v57, v47, v47
	v_mul_f32_e32 v56, v55, v55
	v_fmac_f32_e32 v56, v54, v54
	v_fmac_f32_e32 v57, v46, v46
	v_add_f32_e32 v68, v56, v57
	v_lshlrev_b32_e32 v56, 16, v45
	v_and_b32_e32 v57, 0xffff0000, v45
	v_pk_mul_f32 v[64:65], v[44:45], v[66:67] op_sel_hi:[0,1]
	v_pk_mul_f32 v[56:57], v[44:45], v[56:57] op_sel_hi:[0,1]
	v_pk_fma_f32 v[52:53], v[8:9], v[56:57], v[52:53]
	v_pk_fma_f32 v[56:57], v[6:7], v[64:65], v[58:59]
	v_mul_f32_e32 v58, v53, v53
	v_mul_f32_e32 v45, v57, v57
	v_fmac_f32_e32 v45, v56, v56
	v_fmac_f32_e32 v58, v52, v52
	v_add_f32_e32 v45, v45, v58
	v_add_f32_e32 v45, v68, v45
	v_lshlrev_b32_e32 v58, 16, v42
	v_and_b32_e32 v59, 0xffff0000, v42
	v_lshlrev_b32_e32 v42, 16, v43
	v_and_b32_e32 v43, 0xffff0000, v43
	v_pk_mul_f32 v[58:59], v[44:45], v[58:59] op_sel_hi:[0,1]
	v_pk_mul_f32 v[42:43], v[44:45], v[42:43] op_sel_hi:[0,1]
	v_pk_fma_f32 v[42:43], v[12:13], v[42:43], v[50:51]
	v_pk_fma_f32 v[50:51], v[10:11], v[58:59], v[60:61]
	v_mul_f32_e32 v59, v43, v43
	v_mul_f32_e32 v58, v51, v51
	v_fmac_f32_e32 v58, v50, v50
	v_fmac_f32_e32 v59, v42, v42
	v_add_f32_e32 v58, v58, v59
	v_add_f32_e32 v60, v58, v45
	v_lshlrev_b32_e32 v58, 16, v40
	v_and_b32_e32 v59, 0xffff0000, v40
	v_lshlrev_b32_e32 v40, 16, v41
	v_and_b32_e32 v41, 0xffff0000, v41
	v_pk_mul_f32 v[58:59], v[44:45], v[58:59] op_sel_hi:[0,1]
	v_pk_mul_f32 v[40:41], v[44:45], v[40:41] op_sel_hi:[0,1]
	v_pk_fma_f32 v[44:45], v[16:17], v[40:41], v[48:49]
	v_pk_fma_f32 v[48:49], v[14:15], v[58:59], v[62:63]
	v_mul_f32_e32 v41, v45, v45
	v_mul_f32_e32 v40, v49, v49
	v_fmac_f32_e32 v40, v48, v48
	v_fmac_f32_e32 v41, v44, v44
	v_add_f32_e32 v40, v40, v41
	v_add_f32_e32 v40, v40, v60
	v_lshl_add_u64 v[58:59], v[22:23], 0, s[10:11]
	s_mov_b64 s[10:11], 0x2d001200
	v_lshl_add_u64 v[60:61], v[22:23], 0, s[10:11]
	s_mov_b64 s[10:11], 0x2d001400
	v_add_f32_dpp v40, v40, v40 quad_perm:[1,0,3,2] row_mask:0xf bank_mask:0xf
	v_lshl_add_u64 v[62:63], v[22:23], 0, s[10:11]
	s_mov_b64 s[10:11], 0x2d001600
	v_cvt_pk_bf16_f32 v54, v54, v55
	v_cvt_pk_bf16_f32 v55, v46, v47
	v_add_f32_dpp v40, v40, v40 quad_perm:[2,3,0,1] row_mask:0xf bank_mask:0xf
	v_cvt_pk_bf16_f32 v46, v56, v57
	v_cvt_pk_bf16_f32 v47, v52, v53
	v_lshl_add_u64 v[64:65], v[22:23], 0, s[10:11]
	global_store_dwordx2 v[60:61], v[46:47], off
	v_add_f32_dpp v40, v40, v40 row_half_mirror row_mask:0xf bank_mask:0xf
	v_cvt_pk_bf16_f32 v46, v50, v51
	v_cvt_pk_bf16_f32 v47, v42, v43
	v_cvt_pk_bf16_f32 v42, v48, v49
	v_cvt_pk_bf16_f32 v43, v44, v45
	v_add_f32_dpp v40, v40, v40 row_mirror row_mask:0xf bank_mask:0xf
	v_mov_b32_e32 v41, v40
	v_mov_b32_e32 v254, v40
	s_nop 1
	v_permlane16_swap_b32_e32 v41, v254
	global_store_dwordx2 v[58:59], v[54:55], off
	global_store_dwordx2 v[62:63], v[46:47], off
	global_store_dwordx2 v[64:65], v[42:43], off
	v_add_f32_e32 v40, v254, v41
	v_mov_b32_e32 v41, v40
	v_mov_b32_e32 v254, v40
	s_nop 1
	v_permlane32_swap_b32_e32 v41, v254
	s_and_saveexec_b64 s[10:11], s[4:5]
	s_cbranch_execz .LBB0_880
	v_add_f32_e32 v40, v254, v41
	v_fmamk_f32 v40, v40, 0x3a800000, v241
	v_mul_f32_e32 v41, 0x4b800000, v40
	v_cmp_gt_f32_e32 vcc, s21, v40
	s_add_u32 s7, s0, s8
	s_addc_u32 s12, s1, s9
	v_cndmask_b32_e32 v40, v40, v41, vcc
	v_rsq_f32_e32 v40, v40
	s_nop 0
	v_mul_f32_e32 v41, 0x45800000, v40
	v_cndmask_b32_e32 v42, v40, v41, vcc
	v_mov_b32_e32 v40, s7
	v_add_co_u32_e32 v40, vcc, 0x3b700000, v40
	v_mov_b32_e32 v41, s12
	s_nop 0
	v_addc_co_u32_e32 v41, vcc, 0, v41, vcc
	global_store_dword v[40:41], v42, off offset:8
; __device__ __forceinline__ unsigned cvtpk(float lo, float hi) { f32x2 v = {lo, hi}; bf16x2_t b = __builtin_convertvector(v, bf16x2_t); return __builtin_bit_cast(unsigned, b); }
; __device__ __forceinline__ float bflo(unsigned u) { return __uint_as_float(u << 16); }
; __device__ __forceinline__ float bfhi(unsigned u) { return __uint_as_float(u & 0xffff0000u); }
; template <int NR, bool XBF, bool WOUT, bool WXB = true>
; __device__ __forceinline__ void rows_final(const float* xp, const float* xs, const bf16_t* __restrict__ Y, const float* __restrict__ ss, const float* __restrict__ gpost, float* out, bf16_t* xb, float* rs, int row0, int lane) {
;     ...
;     for (int r = 0; r < NR; ++r) { const int row = row0 + r;
;         const float rn = rsqrtf(wave_sum(ssl[r]) * (1.f / DM) + EPS); float s = 0.f;
; #pragma unroll
;         for (int j = 0; j < 4; ++j) { const f32x4 yf = {bflo(yy[r][j].x), bfhi(yy[r][j].x), bflo(yy[r][j].y), bfhi(yy[r][j].y)};
;             v[r][j] = v[r][j] + yf * rn * g[j]; s += (v[r][j][0] * v[r][j][0] + v[r][j][1] * v[r][j][1]) + (v[r][j][2] * v[r][j][2] + v[r][j][3] * v[r][j][3]); }
;         s = wave_sum(s);
;         f32x4* oo = (f32x4*)(out + (size_t)row * DM) + lane; u32x2* o = (u32x2*)(xb + (size_t)row * DM) + lane;
; #pragma unroll
;         for (int j = 0; j < 4; ++j) { if (WOUT) oo[64 * j] = v[r][j]; if (WXB) { u32x2 w; w.x = cvtpk(v[r][j][0], v[r][j][1]); w.y = cvtpk(v[r][j][2], v[r][j][3]); o[64 * j] = w; } }
;         if (WXB && lane == 0) rs[row] = rsqrtf(s * (1.f / DM) + EPS); }
.LBB0_880:
	s_or_b64 exec, exec, s[10:11]
	s_waitcnt vmcnt(0)
	v_and_b32_e32 v41, 0xffff0000, v38
	s_mov_b64 s[10:11], 0x2d001800
	v_add_f32_dpp v42, v85, v85 quad_perm:[1,0,3,2] row_mask:0xf bank_mask:0xf
	v_lshlrev_b32_e32 v40, 16, v38
	v_lshlrev_b32_e32 v38, 16, v39
	v_and_b32_e32 v39, 0xffff0000, v39
	v_add_f32_dpp v44, v42, v42 quad_perm:[2,3,0,1] row_mask:0xf bank_mask:0xf
	v_lshlrev_b32_e32 v42, 16, v36
	v_and_b32_e32 v43, 0xffff0000, v36
	v_lshlrev_b32_e32 v36, 16, v37
	v_and_b32_e32 v37, 0xffff0000, v37
	v_add_f32_dpp v46, v44, v44 row_half_mirror row_mask:0xf bank_mask:0xf
	v_lshlrev_b32_e32 v44, 16, v34
	v_and_b32_e32 v45, 0xffff0000, v34
	v_lshlrev_b32_e32 v34, 16, v35
	v_and_b32_e32 v35, 0xffff0000, v35
	v_add_f32_dpp v48, v46, v46 row_mirror row_mask:0xf bank_mask:0xf
	v_mov_b32_e32 v49, v48
	v_mov_b32_e32 v254, v48
	s_nop 1
	v_permlane16_swap_b32_e32 v49, v254
	v_lshlrev_b32_e32 v46, 16, v32
	v_and_b32_e32 v47, 0xffff0000, v32
	v_lshlrev_b32_e32 v32, 16, v33
	v_and_b32_e32 v33, 0xffff0000, v33
	v_add_f32_e32 v50, v254, v49
	v_mov_b32_e32 v51, v50
	v_mov_b32_e32 v254, v50
	s_nop 1
	v_permlane32_swap_b32_e32 v51, v254
	v_lshlrev_b32_e32 v48, 16, v30
	v_and_b32_e32 v49, 0xffff0000, v30
	v_lshlrev_b32_e32 v30, 16, v31
	v_and_b32_e32 v31, 0xffff0000, v31
	v_add_f32_e32 v50, v254, v51
	v_fmamk_f32 v50, v50, 0x3a800000, v241
	v_mul_f32_e32 v51, 0x4b800000, v50
	v_cmp_gt_f32_e32 vcc, s21, v50
	s_nop 1
	v_cndmask_b32_e32 v50, v50, v51, vcc
	v_rsq_f32_e32 v52, v50
	v_lshlrev_b32_e32 v50, 16, v28
	v_and_b32_e32 v51, 0xffff0000, v28
	v_mul_f32_e32 v28, 0x45800000, v52
	v_cndmask_b32_e32 v28, v52, v28, vcc
	v_pk_mul_f32 v[48:49], v[28:29], v[48:49] op_sel_hi:[0,1]
	v_pk_mul_f32 v[30:31], v[28:29], v[30:31] op_sel_hi:[0,1]
	v_pk_fma_f32 v[30:31], v[4:5], v[30:31], v[38:39]
	v_pk_fma_f32 v[38:39], v[2:3], v[48:49], v[40:41]
	v_mul_f32_e32 v41, v31, v31
	v_mul_f32_e32 v40, v39, v39
	v_fmac_f32_e32 v40, v38, v38
	v_fmac_f32_e32 v41, v30, v30
	v_add_f32_e32 v52, v40, v41
	v_lshlrev_b32_e32 v40, 16, v29
	v_and_b32_e32 v41, 0xffff0000, v29
	v_pk_mul_f32 v[48:49], v[28:29], v[50:51] op_sel_hi:[0,1]
	v_pk_mul_f32 v[40:41], v[28:29], v[40:41] op_sel_hi:[0,1]
	v_pk_fma_f32 v[36:37], v[8:9], v[40:41], v[36:37]
	v_pk_fma_f32 v[40:41], v[6:7], v[48:49], v[42:43]
	v_mul_f32_e32 v42, v37, v37
	v_mul_f32_e32 v29, v41, v41
	v_fmac_f32_e32 v29, v40, v40
	v_fmac_f32_e32 v42, v36, v36
	v_add_f32_e32 v29, v29, v42
	v_add_f32_e32 v29, v52, v29
	v_lshlrev_b32_e32 v42, 16, v26
	v_and_b32_e32 v43, 0xffff0000, v26
	v_lshlrev_b32_e32 v26, 16, v27
	v_and_b32_e32 v27, 0xffff0000, v27
	v_pk_mul_f32 v[42:43], v[28:29], v[42:43] op_sel_hi:[0,1]
	v_pk_mul_f32 v[26:27], v[28:29], v[26:27] op_sel_hi:[0,1]
	v_pk_fma_f32 v[26:27], v[12:13], v[26:27], v[34:35]
	v_pk_fma_f32 v[34:35], v[10:11], v[42:43], v[44:45]
	v_mul_f32_e32 v43, v27, v27
	v_mul_f32_e32 v42, v35, v35
	v_fmac_f32_e32 v42, v34, v34
	v_fmac_f32_e32 v43, v26, v26
	v_add_f32_e32 v42, v42, v43
	v_add_f32_e32 v44, v42, v29
	v_lshlrev_b32_e32 v42, 16, v24
	v_and_b32_e32 v43, 0xffff0000, v24
	v_lshlrev_b32_e32 v24, 16, v25
	v_and_b32_e32 v25, 0xffff0000, v25
	v_pk_mul_f32 v[42:43], v[28:29], v[42:43] op_sel_hi:[0,1]
	v_pk_mul_f32 v[24:25], v[28:29], v[24:25] op_sel_hi:[0,1]
	v_pk_fma_f32 v[24:25], v[16:17], v[24:25], v[32:33]
	v_pk_fma_f32 v[28:29], v[14:15], v[42:43], v[46:47]
	v_mul_f32_e32 v33, v25, v25
	v_mul_f32_e32 v32, v29, v29
	v_fmac_f32_e32 v32, v28, v28
	v_fmac_f32_e32 v33, v24, v24
	v_add_f32_e32 v32, v32, v33
	v_add_f32_e32 v32, v32, v44
	v_cvt_pk_bf16_f32 v38, v38, v39
	v_cvt_pk_bf16_f32 v39, v30, v31
	v_cvt_pk_bf16_f32 v30, v40, v41
	v_cvt_pk_bf16_f32 v31, v36, v37
	v_add_f32_dpp v32, v32, v32 quad_perm:[1,0,3,2] row_mask:0xf bank_mask:0xf
	s_nop 1
	v_add_f32_dpp v32, v32, v32 quad_perm:[2,3,0,1] row_mask:0xf bank_mask:0xf
	s_nop 1
	v_add_f32_dpp v32, v32, v32 row_half_mirror row_mask:0xf bank_mask:0xf
	s_nop 1
	v_add_f32_dpp v48, v32, v32 row_mirror row_mask:0xf bank_mask:0xf
	v_mov_b32_e32 v49, v48
	v_mov_b32_e32 v254, v48
	s_nop 1
	v_permlane16_swap_b32_e32 v49, v254
	v_lshl_add_u64 v[32:33], v[22:23], 0, s[10:11]
	s_mov_b64 s[10:11], 0x2d001a00
	v_lshl_add_u64 v[42:43], v[22:23], 0, s[10:11]
	s_mov_b64 s[10:11], 0x2d001c00
	v_lshl_add_u64 v[44:45], v[22:23], 0, s[10:11]
	s_mov_b64 s[10:11], 0x2d001e00
	v_lshl_add_u64 v[46:47], v[22:23], 0, s[10:11]
	v_add_f32_e32 v22, v254, v49
	v_mov_b32_e32 v23, v22
	v_mov_b32_e32 v254, v22
	s_nop 1
	v_permlane32_swap_b32_e32 v23, v254
	global_store_dwordx2 v[42:43], v[30:31], off
	v_cvt_pk_bf16_f32 v30, v34, v35
	v_cvt_pk_bf16_f32 v31, v26, v27
	v_cvt_pk_bf16_f32 v26, v28, v29
	v_cvt_pk_bf16_f32 v27, v24, v25
	global_store_dwordx2 v[32:33], v[38:39], off
	global_store_dwordx2 v[44:45], v[30:31], off
	global_store_dwordx2 v[46:47], v[26:27], off
	s_and_saveexec_b64 s[10:11], s[4:5]
	s_cbranch_execz .LBB0_865
	v_add_f32_e32 v22, v254, v23
	v_fmamk_f32 v22, v22, 0x3a800000, v241
	v_mul_f32_e32 v23, 0x4b800000, v22
	v_cmp_gt_f32_e32 vcc, s21, v22
	s_add_u32 s7, s0, s8
	s_addc_u32 s12, s1, s9
	v_cndmask_b32_e32 v22, v22, v23, vcc
	v_rsq_f32_e32 v22, v22
	s_nop 0
	v_mul_f32_e32 v23, 0x45800000, v22
	v_cndmask_b32_e32 v24, v22, v23, vcc
	v_mov_b32_e32 v22, s7
	v_add_co_u32_e32 v22, vcc, 0x3b700000, v22
	v_mov_b32_e32 v23, s12
	s_nop 0
	v_addc_co_u32_e32 v23, vcc, 0, v23, vcc
	global_store_dword v[22:23], v24, off offset:12
	s_branch .LBB0_865
